# P0: modulation GEMV weight-row loads software-pipelined (2 register sets), small-weight conversion rebalanced toward the 1-item workgroups; SWA q-fragment wait hoisted out of the tile loop
# speedup vs baseline: 1.0109x; 1.0062x over previous
.LBB0_27:
	s_or_b64 exec, exec, s[74:75]
	s_ashr_i32 s73, s72, 31
	s_lshl_b64 s[26:27], s[72:73], 11
	s_add_u32 s26, s26, s82
	s_addc_u32 s27, s27, s63
	s_add_u32 s26, s26, s64
	s_addc_u32 s27, s27, 0
	s_mul_i32 s27, s27, 0xc000
	s_mul_hi_u32 s28, s26, 0xc000
	s_add_i32 s29, s28, s27
	s_mul_i32 s28, s26, 0xc000
	s_lshl_b32 s26, s67, 6
	s_and_b32 s26, s26, 0xffffff00
	s_ashr_i32 s27, s26, 31
	s_lshl_b64 s[26:27], s[26:27], 2
	s_add_u32 s28, s28, s26
	s_addc_u32 s29, s29, s27
	v_mov_b32_e32 v20, 0
	v_lshl_add_u64 v[42:43], v[40:41], 0, s[28:29]
	s_mov_b64 s[28:29], 0
	v_lshl_add_u64 v[44:45], v[42:43], 0, s[28:29]
	v_add_co_u32_e32 v132, vcc, s94, v44
	s_mov_b32 s31, 0x18000
	s_nop 0
	v_addc_co_u32_e32 v133, vcc, 0, v45, vcc
	v_add_co_u32_e32 v136, vcc, s31, v44
	s_mov_b32 s64, 0x24000
	s_nop 0
	v_addc_co_u32_e32 v137, vcc, 0, v45, vcc
	v_add_co_u32_e32 v140, vcc, s64, v44
	s_mov_b32 s65, 0x30000
	s_nop 0
	v_addc_co_u32_e32 v141, vcc, 0, v45, vcc
	global_load_dwordx4 v[56:59], v[44:45], off nt
	v_add_co_u32_e32 v144, vcc, s65, v44
	s_mov_b32 s67, 0x3c000
	s_nop 0
	v_addc_co_u32_e32 v145, vcc, 0, v45, vcc
	v_add_co_u32_e32 v148, vcc, s67, v44
	s_mov_b32 s73, 0x48000
	s_nop 0
	v_addc_co_u32_e32 v149, vcc, 0, v45, vcc
	v_add_co_u32_e32 v152, vcc, s73, v44
	s_nop 0
	v_addc_co_u32_e32 v153, vcc, 0, v45, vcc
	v_add_co_u32_e32 v44, vcc, s95, v44
	v_addc_co_u32_e32 v45, vcc, 0, v45, vcc
	global_load_dwordx4 v[132:135], v[132:133], off nt
	s_nop 0
	global_load_dwordx4 v[136:139], v[136:137], off nt
	s_nop 0
	global_load_dwordx4 v[140:143], v[140:141], off nt
	s_nop 0
	global_load_dwordx4 v[144:147], v[144:145], off nt
	s_nop 0
	global_load_dwordx4 v[148:151], v[148:149], off nt
	s_nop 0
	global_load_dwordx4 v[152:155], v[152:153], off nt
	s_nop 0
	global_load_dwordx4 v[156:159], v[44:45], off nt
	s_mov_b32 s30, s85
	v_mov_b32_e32 v21, v20
	v_mov_b32_e32 v22, v20
	v_mov_b32_e32 v23, v20
	v_mov_b32_e32 v32, v20
	v_mov_b32_e32 v33, v20
	v_mov_b32_e32 v34, v20
	v_mov_b32_e32 v35, v20
	v_mov_b32_e32 v28, v20
	v_mov_b32_e32 v29, v20
	v_mov_b32_e32 v30, v20
	v_mov_b32_e32 v31, v20
	v_mov_b32_e32 v24, v20
	v_mov_b32_e32 v25, v20
	v_mov_b32_e32 v26, v20
	v_mov_b32_e32 v27, v20
	v_mov_b32_e32 v16, v20
	v_mov_b32_e32 v17, v20
	v_mov_b32_e32 v18, v20
	v_mov_b32_e32 v19, v20
	v_mov_b32_e32 v12, v20
	v_mov_b32_e32 v13, v20
	v_mov_b32_e32 v14, v20
	v_mov_b32_e32 v15, v20
	v_mov_b32_e32 v8, v20
	v_mov_b32_e32 v9, v20
	v_mov_b32_e32 v10, v20
	v_mov_b32_e32 v11, v20
	v_mov_b32_e32 v4, v20
	v_mov_b32_e32 v5, v20
	v_mov_b32_e32 v6, v20
	v_mov_b32_e32 v7, v20
	v_mov_b32_e32 v0, v20
	v_mov_b32_e32 v1, v20
	v_mov_b32_e32 v2, v20
	v_mov_b32_e32 v3, v20
	s_waitcnt lgkmcnt(0)
	s_barrier
.LBB0_28:
	s_add_u32 s28, s28, 0x60000
	s_addc_u32 s29, s29, 0
	v_lshl_add_u64 v[44:45], v[42:43], 0, s[28:29]
	v_add_co_u32_e32 v196, vcc, s94, v44
	s_mov_b32 s31, 0x18000
	s_nop 0
	v_addc_co_u32_e32 v197, vcc, 0, v45, vcc
	v_add_co_u32_e32 v200, vcc, s31, v44
	s_mov_b32 s64, 0x24000
	s_nop 0
	v_addc_co_u32_e32 v201, vcc, 0, v45, vcc
	v_add_co_u32_e32 v204, vcc, s64, v44
	s_mov_b32 s65, 0x30000
	s_nop 0
	v_addc_co_u32_e32 v205, vcc, 0, v45, vcc
	global_load_dwordx4 v[192:195], v[44:45], off nt
	v_add_co_u32_e32 v208, vcc, s65, v44
	s_mov_b32 s67, 0x3c000
	s_nop 0
	v_addc_co_u32_e32 v209, vcc, 0, v45, vcc
	v_add_co_u32_e32 v212, vcc, s67, v44
	s_mov_b32 s73, 0x48000
	s_nop 0
	v_addc_co_u32_e32 v213, vcc, 0, v45, vcc
	v_add_co_u32_e32 v216, vcc, s73, v44
	v_mov_b32_e32 v38, s30
	s_nop 0
	v_addc_co_u32_e32 v217, vcc, 0, v45, vcc
	v_add_co_u32_e32 v44, vcc, s95, v44
	ds_read_b128 v[60:63], v38
	ds_read_b128 v[64:67], v38 offset:16
	ds_read_b128 v[68:71], v38 offset:2048
	ds_read_b128 v[72:75], v38 offset:2064
	ds_read_b128 v[76:79], v38 offset:4096
	ds_read_b128 v[80:83], v38 offset:4112
	ds_read_b128 v[84:87], v38 offset:6144
	ds_read_b128 v[88:91], v38 offset:6160
	ds_read_b128 v[92:95], v38 offset:8192
	ds_read_b128 v[96:99], v38 offset:8208
	ds_read_b128 v[100:103], v38 offset:10240
	ds_read_b128 v[104:107], v38 offset:10256
	ds_read_b128 v[108:111], v38 offset:12288
	ds_read_b128 v[112:115], v38 offset:12304
	ds_read_b128 v[116:119], v38 offset:14336
	ds_read_b128 v[120:123], v38 offset:14352
	ds_read_b128 v[124:127], v38 offset:16384
	ds_read_b128 v[128:131], v38 offset:16400
	v_addc_co_u32_e32 v45, vcc, 0, v45, vcc
	global_load_dwordx4 v[196:199], v[196:197], off nt
	s_nop 0
	global_load_dwordx4 v[200:203], v[200:201], off nt
	s_nop 0
	global_load_dwordx4 v[204:207], v[204:205], off nt
	s_nop 0
	global_load_dwordx4 v[208:211], v[208:209], off nt
	s_nop 0
	global_load_dwordx4 v[212:215], v[212:213], off nt
	s_nop 0
	global_load_dwordx4 v[216:219], v[216:217], off nt
	s_nop 0
	global_load_dwordx4 v[220:223], v[44:45], off nt
	s_waitcnt lgkmcnt(14)
	v_mov_b32_e32 v38, v63
	v_mov_b32_e32 v44, v71
	s_waitcnt lgkmcnt(13)
	v_mov_b32_e32 v160, v79
	s_waitcnt lgkmcnt(11)
	v_mov_b32_e32 v162, v87
	s_waitcnt lgkmcnt(9)
	v_mov_b32_e32 v164, v95
	s_waitcnt lgkmcnt(7)
	v_mov_b32_e32 v166, v103
	s_waitcnt lgkmcnt(5)
	v_mov_b32_e32 v168, v111
	s_waitcnt lgkmcnt(3)
	v_mov_b32_e32 v170, v119
	s_waitcnt lgkmcnt(1)
	v_mov_b32_e32 v172, v127
	s_add_i32 s30, s30, 32
	v_mov_b32_e32 v174, v67
	v_mov_b32_e32 v176, v75
	v_mov_b32_e32 v178, v83
	v_mov_b32_e32 v180, v91
	v_mov_b32_e32 v182, v99
	v_mov_b32_e32 v184, v107
	v_mov_b32_e32 v186, v115
	v_mov_b32_e32 v188, v123
	s_waitcnt lgkmcnt(0)
	v_mov_b32_e32 v190, v131
	s_waitcnt vmcnt(15)
	v_pk_fma_f32 v[20:21], v[60:61], v[56:57], v[20:21] op_sel_hi:[0,1,1]
	v_pk_fma_f32 v[22:23], v[60:61], v[58:59], v[22:23] op_sel_hi:[0,1,1]
	v_pk_fma_f32 v[32:33], v[56:57], v[68:69], v[32:33] op_sel_hi:[1,0,1]
	v_pk_fma_f32 v[34:35], v[58:59], v[68:69], v[34:35] op_sel_hi:[1,0,1]
	v_pk_fma_f32 v[28:29], v[56:57], v[76:77], v[28:29] op_sel_hi:[1,0,1]
	v_pk_fma_f32 v[30:31], v[58:59], v[76:77], v[30:31] op_sel_hi:[1,0,1]
	v_pk_fma_f32 v[24:25], v[56:57], v[84:85], v[24:25] op_sel_hi:[1,0,1]
	v_pk_fma_f32 v[26:27], v[58:59], v[84:85], v[26:27] op_sel_hi:[1,0,1]
	v_pk_fma_f32 v[16:17], v[56:57], v[92:93], v[16:17] op_sel_hi:[1,0,1]
	v_pk_fma_f32 v[18:19], v[58:59], v[92:93], v[18:19] op_sel_hi:[1,0,1]
	v_pk_fma_f32 v[12:13], v[56:57], v[100:101], v[12:13] op_sel_hi:[1,0,1]
	v_pk_fma_f32 v[14:15], v[58:59], v[100:101], v[14:15] op_sel_hi:[1,0,1]
	v_pk_fma_f32 v[8:9], v[56:57], v[108:109], v[8:9] op_sel_hi:[1,0,1]
	v_pk_fma_f32 v[10:11], v[58:59], v[108:109], v[10:11] op_sel_hi:[1,0,1]
	v_pk_fma_f32 v[4:5], v[56:57], v[116:117], v[4:5] op_sel_hi:[1,0,1]
	v_pk_fma_f32 v[6:7], v[58:59], v[116:117], v[6:7] op_sel_hi:[1,0,1]
	v_pk_fma_f32 v[0:1], v[56:57], v[124:125], v[0:1] op_sel_hi:[1,0,1]
	v_pk_fma_f32 v[2:3], v[58:59], v[124:125], v[2:3] op_sel_hi:[1,0,1]
	s_waitcnt vmcnt(14)
	v_pk_fma_f32 v[20:21], v[60:61], v[132:133], v[20:21] op_sel:[1,0,0]
	v_pk_fma_f32 v[22:23], v[60:61], v[134:135], v[22:23] op_sel:[1,0,0]
	v_pk_fma_f32 v[32:33], v[132:133], v[68:69], v[32:33] op_sel:[0,1,0]
	v_pk_fma_f32 v[34:35], v[134:135], v[68:69], v[34:35] op_sel:[0,1,0]
	v_pk_fma_f32 v[28:29], v[132:133], v[76:77], v[28:29] op_sel:[0,1,0]
	v_pk_fma_f32 v[30:31], v[134:135], v[76:77], v[30:31] op_sel:[0,1,0]
	v_pk_fma_f32 v[24:25], v[132:133], v[84:85], v[24:25] op_sel:[0,1,0]
	v_pk_fma_f32 v[26:27], v[134:135], v[84:85], v[26:27] op_sel:[0,1,0]
	v_pk_fma_f32 v[16:17], v[132:133], v[92:93], v[16:17] op_sel:[0,1,0]
	v_pk_fma_f32 v[18:19], v[134:135], v[92:93], v[18:19] op_sel:[0,1,0]
	v_pk_fma_f32 v[12:13], v[132:133], v[100:101], v[12:13] op_sel:[0,1,0]
	v_pk_fma_f32 v[14:15], v[134:135], v[100:101], v[14:15] op_sel:[0,1,0]
	v_pk_fma_f32 v[8:9], v[132:133], v[108:109], v[8:9] op_sel:[0,1,0]
	v_pk_fma_f32 v[10:11], v[134:135], v[108:109], v[10:11] op_sel:[0,1,0]
	v_pk_fma_f32 v[4:5], v[132:133], v[116:117], v[4:5] op_sel:[0,1,0]
	v_pk_fma_f32 v[6:7], v[134:135], v[116:117], v[6:7] op_sel:[0,1,0]
	v_pk_fma_f32 v[0:1], v[132:133], v[124:125], v[0:1] op_sel:[0,1,0]
	v_pk_fma_f32 v[2:3], v[134:135], v[124:125], v[2:3] op_sel:[0,1,0]
	s_waitcnt vmcnt(13)
	v_pk_fma_f32 v[20:21], v[62:63], v[136:137], v[20:21] op_sel_hi:[0,1,1]
	v_pk_fma_f32 v[22:23], v[62:63], v[138:139], v[22:23] op_sel_hi:[0,1,1]
	v_pk_fma_f32 v[32:33], v[136:137], v[70:71], v[32:33] op_sel_hi:[1,0,1]
	v_pk_fma_f32 v[34:35], v[138:139], v[70:71], v[34:35] op_sel_hi:[1,0,1]
	v_pk_fma_f32 v[28:29], v[136:137], v[78:79], v[28:29] op_sel_hi:[1,0,1]
	v_pk_fma_f32 v[30:31], v[138:139], v[78:79], v[30:31] op_sel_hi:[1,0,1]
	v_pk_fma_f32 v[24:25], v[136:137], v[86:87], v[24:25] op_sel_hi:[1,0,1]
	v_pk_fma_f32 v[26:27], v[138:139], v[86:87], v[26:27] op_sel_hi:[1,0,1]
	v_pk_fma_f32 v[16:17], v[136:137], v[94:95], v[16:17] op_sel_hi:[1,0,1]
	v_pk_fma_f32 v[18:19], v[138:139], v[94:95], v[18:19] op_sel_hi:[1,0,1]
	v_pk_fma_f32 v[12:13], v[136:137], v[102:103], v[12:13] op_sel_hi:[1,0,1]
	v_pk_fma_f32 v[14:15], v[138:139], v[102:103], v[14:15] op_sel_hi:[1,0,1]
	v_pk_fma_f32 v[8:9], v[136:137], v[110:111], v[8:9] op_sel_hi:[1,0,1]
	v_pk_fma_f32 v[10:11], v[138:139], v[110:111], v[10:11] op_sel_hi:[1,0,1]
	v_pk_fma_f32 v[4:5], v[136:137], v[118:119], v[4:5] op_sel_hi:[1,0,1]
	v_pk_fma_f32 v[6:7], v[138:139], v[118:119], v[6:7] op_sel_hi:[1,0,1]
	v_pk_fma_f32 v[0:1], v[136:137], v[126:127], v[0:1] op_sel_hi:[1,0,1]
	v_pk_fma_f32 v[2:3], v[138:139], v[126:127], v[2:3] op_sel_hi:[1,0,1]
	s_waitcnt vmcnt(12)
	v_pk_fma_f32 v[20:21], v[38:39], v[140:141], v[20:21] op_sel_hi:[0,1,1]
	v_pk_fma_f32 v[22:23], v[38:39], v[142:143], v[22:23] op_sel_hi:[0,1,1]
	v_pk_fma_f32 v[32:33], v[140:141], v[44:45], v[32:33] op_sel_hi:[1,0,1]
	v_pk_fma_f32 v[34:35], v[142:143], v[44:45], v[34:35] op_sel_hi:[1,0,1]
	v_pk_fma_f32 v[28:29], v[140:141], v[160:161], v[28:29] op_sel_hi:[1,0,1]
	v_pk_fma_f32 v[30:31], v[142:143], v[160:161], v[30:31] op_sel_hi:[1,0,1]
	v_pk_fma_f32 v[24:25], v[140:141], v[162:163], v[24:25] op_sel_hi:[1,0,1]
	v_pk_fma_f32 v[26:27], v[142:143], v[162:163], v[26:27] op_sel_hi:[1,0,1]
	v_pk_fma_f32 v[16:17], v[140:141], v[164:165], v[16:17] op_sel_hi:[1,0,1]
	v_pk_fma_f32 v[18:19], v[142:143], v[164:165], v[18:19] op_sel_hi:[1,0,1]
	v_pk_fma_f32 v[12:13], v[140:141], v[166:167], v[12:13] op_sel_hi:[1,0,1]
	v_pk_fma_f32 v[14:15], v[142:143], v[166:167], v[14:15] op_sel_hi:[1,0,1]
	v_pk_fma_f32 v[8:9], v[140:141], v[168:169], v[8:9] op_sel_hi:[1,0,1]
	v_pk_fma_f32 v[10:11], v[142:143], v[168:169], v[10:11] op_sel_hi:[1,0,1]
	v_pk_fma_f32 v[4:5], v[140:141], v[170:171], v[4:5] op_sel_hi:[1,0,1]
	v_pk_fma_f32 v[6:7], v[142:143], v[170:171], v[6:7] op_sel_hi:[1,0,1]
	v_pk_fma_f32 v[0:1], v[140:141], v[172:173], v[0:1] op_sel_hi:[1,0,1]
	v_pk_fma_f32 v[2:3], v[142:143], v[172:173], v[2:3] op_sel_hi:[1,0,1]
	s_waitcnt vmcnt(11)
	v_pk_fma_f32 v[20:21], v[64:65], v[144:145], v[20:21] op_sel_hi:[0,1,1]
	v_pk_fma_f32 v[22:23], v[64:65], v[146:147], v[22:23] op_sel_hi:[0,1,1]
	v_pk_fma_f32 v[32:33], v[144:145], v[72:73], v[32:33] op_sel_hi:[1,0,1]
	v_pk_fma_f32 v[34:35], v[146:147], v[72:73], v[34:35] op_sel_hi:[1,0,1]
	v_pk_fma_f32 v[28:29], v[144:145], v[80:81], v[28:29] op_sel_hi:[1,0,1]
	v_pk_fma_f32 v[30:31], v[146:147], v[80:81], v[30:31] op_sel_hi:[1,0,1]
	v_pk_fma_f32 v[24:25], v[144:145], v[88:89], v[24:25] op_sel_hi:[1,0,1]
	v_pk_fma_f32 v[26:27], v[146:147], v[88:89], v[26:27] op_sel_hi:[1,0,1]
	v_pk_fma_f32 v[16:17], v[144:145], v[96:97], v[16:17] op_sel_hi:[1,0,1]
	v_pk_fma_f32 v[18:19], v[146:147], v[96:97], v[18:19] op_sel_hi:[1,0,1]
	v_pk_fma_f32 v[12:13], v[144:145], v[104:105], v[12:13] op_sel_hi:[1,0,1]
	v_pk_fma_f32 v[14:15], v[146:147], v[104:105], v[14:15] op_sel_hi:[1,0,1]
	v_pk_fma_f32 v[8:9], v[144:145], v[112:113], v[8:9] op_sel_hi:[1,0,1]
	v_pk_fma_f32 v[10:11], v[146:147], v[112:113], v[10:11] op_sel_hi:[1,0,1]
	v_pk_fma_f32 v[4:5], v[144:145], v[120:121], v[4:5] op_sel_hi:[1,0,1]
	v_pk_fma_f32 v[6:7], v[146:147], v[120:121], v[6:7] op_sel_hi:[1,0,1]
	v_pk_fma_f32 v[0:1], v[144:145], v[128:129], v[0:1] op_sel_hi:[1,0,1]
	v_pk_fma_f32 v[2:3], v[146:147], v[128:129], v[2:3] op_sel_hi:[1,0,1]
	s_waitcnt vmcnt(10)
	v_pk_fma_f32 v[20:21], v[64:65], v[148:149], v[20:21] op_sel:[1,0,0]
	v_pk_fma_f32 v[22:23], v[64:65], v[150:151], v[22:23] op_sel:[1,0,0]
	v_pk_fma_f32 v[32:33], v[148:149], v[72:73], v[32:33] op_sel:[0,1,0]
	v_pk_fma_f32 v[34:35], v[150:151], v[72:73], v[34:35] op_sel:[0,1,0]
	v_pk_fma_f32 v[28:29], v[148:149], v[80:81], v[28:29] op_sel:[0,1,0]
	v_pk_fma_f32 v[30:31], v[150:151], v[80:81], v[30:31] op_sel:[0,1,0]
	v_pk_fma_f32 v[24:25], v[148:149], v[88:89], v[24:25] op_sel:[0,1,0]
	v_pk_fma_f32 v[26:27], v[150:151], v[88:89], v[26:27] op_sel:[0,1,0]
	v_pk_fma_f32 v[16:17], v[148:149], v[96:97], v[16:17] op_sel:[0,1,0]
	v_pk_fma_f32 v[18:19], v[150:151], v[96:97], v[18:19] op_sel:[0,1,0]
	v_pk_fma_f32 v[12:13], v[148:149], v[104:105], v[12:13] op_sel:[0,1,0]
	v_pk_fma_f32 v[14:15], v[150:151], v[104:105], v[14:15] op_sel:[0,1,0]
	v_pk_fma_f32 v[8:9], v[148:149], v[112:113], v[8:9] op_sel:[0,1,0]
	v_pk_fma_f32 v[10:11], v[150:151], v[112:113], v[10:11] op_sel:[0,1,0]
	v_pk_fma_f32 v[4:5], v[148:149], v[120:121], v[4:5] op_sel:[0,1,0]
	v_pk_fma_f32 v[6:7], v[150:151], v[120:121], v[6:7] op_sel:[0,1,0]
	v_pk_fma_f32 v[0:1], v[148:149], v[128:129], v[0:1] op_sel:[0,1,0]
	v_pk_fma_f32 v[2:3], v[150:151], v[128:129], v[2:3] op_sel:[0,1,0]
	s_waitcnt vmcnt(9)
	v_pk_fma_f32 v[20:21], v[66:67], v[152:153], v[20:21] op_sel_hi:[0,1,1]
	v_pk_fma_f32 v[22:23], v[66:67], v[154:155], v[22:23] op_sel_hi:[0,1,1]
	v_pk_fma_f32 v[32:33], v[152:153], v[74:75], v[32:33] op_sel_hi:[1,0,1]
	v_pk_fma_f32 v[34:35], v[154:155], v[74:75], v[34:35] op_sel_hi:[1,0,1]
	v_pk_fma_f32 v[28:29], v[152:153], v[82:83], v[28:29] op_sel_hi:[1,0,1]
	v_pk_fma_f32 v[30:31], v[154:155], v[82:83], v[30:31] op_sel_hi:[1,0,1]
	v_pk_fma_f32 v[24:25], v[152:153], v[90:91], v[24:25] op_sel_hi:[1,0,1]
	v_pk_fma_f32 v[26:27], v[154:155], v[90:91], v[26:27] op_sel_hi:[1,0,1]
	v_pk_fma_f32 v[16:17], v[152:153], v[98:99], v[16:17] op_sel_hi:[1,0,1]
	v_pk_fma_f32 v[18:19], v[154:155], v[98:99], v[18:19] op_sel_hi:[1,0,1]
	v_pk_fma_f32 v[12:13], v[152:153], v[106:107], v[12:13] op_sel_hi:[1,0,1]
	v_pk_fma_f32 v[14:15], v[154:155], v[106:107], v[14:15] op_sel_hi:[1,0,1]
	v_pk_fma_f32 v[8:9], v[152:153], v[114:115], v[8:9] op_sel_hi:[1,0,1]
	v_pk_fma_f32 v[10:11], v[154:155], v[114:115], v[10:11] op_sel_hi:[1,0,1]
	v_pk_fma_f32 v[4:5], v[152:153], v[122:123], v[4:5] op_sel_hi:[1,0,1]
	v_pk_fma_f32 v[6:7], v[154:155], v[122:123], v[6:7] op_sel_hi:[1,0,1]
	v_pk_fma_f32 v[0:1], v[152:153], v[130:131], v[0:1] op_sel_hi:[1,0,1]
	v_pk_fma_f32 v[2:3], v[154:155], v[130:131], v[2:3] op_sel_hi:[1,0,1]
	s_waitcnt vmcnt(8)
	v_pk_fma_f32 v[20:21], v[174:175], v[156:157], v[20:21] op_sel_hi:[0,1,1]
	v_pk_fma_f32 v[22:23], v[174:175], v[158:159], v[22:23] op_sel_hi:[0,1,1]
	v_pk_fma_f32 v[32:33], v[156:157], v[176:177], v[32:33] op_sel_hi:[1,0,1]
	v_pk_fma_f32 v[34:35], v[158:159], v[176:177], v[34:35] op_sel_hi:[1,0,1]
	v_pk_fma_f32 v[28:29], v[156:157], v[178:179], v[28:29] op_sel_hi:[1,0,1]
	v_pk_fma_f32 v[30:31], v[158:159], v[178:179], v[30:31] op_sel_hi:[1,0,1]
	v_pk_fma_f32 v[24:25], v[156:157], v[180:181], v[24:25] op_sel_hi:[1,0,1]
	v_pk_fma_f32 v[26:27], v[158:159], v[180:181], v[26:27] op_sel_hi:[1,0,1]
	v_pk_fma_f32 v[16:17], v[156:157], v[182:183], v[16:17] op_sel_hi:[1,0,1]
	v_pk_fma_f32 v[18:19], v[158:159], v[182:183], v[18:19] op_sel_hi:[1,0,1]
	v_pk_fma_f32 v[12:13], v[156:157], v[184:185], v[12:13] op_sel_hi:[1,0,1]
	v_pk_fma_f32 v[14:15], v[158:159], v[184:185], v[14:15] op_sel_hi:[1,0,1]
	v_pk_fma_f32 v[8:9], v[156:157], v[186:187], v[8:9] op_sel_hi:[1,0,1]
	v_pk_fma_f32 v[10:11], v[158:159], v[186:187], v[10:11] op_sel_hi:[1,0,1]
	v_pk_fma_f32 v[4:5], v[156:157], v[188:189], v[4:5] op_sel_hi:[1,0,1]
	v_pk_fma_f32 v[6:7], v[158:159], v[188:189], v[6:7] op_sel_hi:[1,0,1]
	v_pk_fma_f32 v[0:1], v[156:157], v[190:191], v[0:1] op_sel_hi:[1,0,1]
	v_pk_fma_f32 v[2:3], v[158:159], v[190:191], v[2:3] op_sel_hi:[1,0,1]
	s_add_u32 s28, s28, 0x60000
	s_addc_u32 s29, s29, 0
	v_lshl_add_u64 v[44:45], v[42:43], 0, s[28:29]
	v_add_co_u32_e32 v132, vcc, s94, v44
	s_mov_b32 s31, 0x18000
	s_nop 0
	v_addc_co_u32_e32 v133, vcc, 0, v45, vcc
	v_add_co_u32_e32 v136, vcc, s31, v44
	s_mov_b32 s64, 0x24000
	s_nop 0
	v_addc_co_u32_e32 v137, vcc, 0, v45, vcc
	v_add_co_u32_e32 v140, vcc, s64, v44
	s_mov_b32 s65, 0x30000
	s_nop 0
	v_addc_co_u32_e32 v141, vcc, 0, v45, vcc
	global_load_dwordx4 v[56:59], v[44:45], off nt
	v_add_co_u32_e32 v144, vcc, s65, v44
	s_mov_b32 s67, 0x3c000
	s_nop 0
	v_addc_co_u32_e32 v145, vcc, 0, v45, vcc
	v_add_co_u32_e32 v148, vcc, s67, v44
	s_mov_b32 s73, 0x48000
	s_nop 0
	v_addc_co_u32_e32 v149, vcc, 0, v45, vcc
	v_add_co_u32_e32 v152, vcc, s73, v44
	v_mov_b32_e32 v38, s30
	s_nop 0
	v_addc_co_u32_e32 v153, vcc, 0, v45, vcc
	v_add_co_u32_e32 v44, vcc, s95, v44
	ds_read_b128 v[60:63], v38
	ds_read_b128 v[64:67], v38 offset:16
	ds_read_b128 v[68:71], v38 offset:2048
	ds_read_b128 v[72:75], v38 offset:2064
	ds_read_b128 v[76:79], v38 offset:4096
	ds_read_b128 v[80:83], v38 offset:4112
	ds_read_b128 v[84:87], v38 offset:6144
	ds_read_b128 v[88:91], v38 offset:6160
	ds_read_b128 v[92:95], v38 offset:8192
	ds_read_b128 v[96:99], v38 offset:8208
	ds_read_b128 v[100:103], v38 offset:10240
	ds_read_b128 v[104:107], v38 offset:10256
	ds_read_b128 v[108:111], v38 offset:12288
	ds_read_b128 v[112:115], v38 offset:12304
	ds_read_b128 v[116:119], v38 offset:14336
	ds_read_b128 v[120:123], v38 offset:14352
	ds_read_b128 v[124:127], v38 offset:16384
	ds_read_b128 v[128:131], v38 offset:16400
	v_addc_co_u32_e32 v45, vcc, 0, v45, vcc
	global_load_dwordx4 v[132:135], v[132:133], off nt
	s_nop 0
	global_load_dwordx4 v[136:139], v[136:137], off nt
	s_nop 0
	global_load_dwordx4 v[140:143], v[140:141], off nt
	s_nop 0
	global_load_dwordx4 v[144:147], v[144:145], off nt
	s_nop 0
	global_load_dwordx4 v[148:151], v[148:149], off nt
	s_nop 0
	global_load_dwordx4 v[152:155], v[152:153], off nt
	s_nop 0
	global_load_dwordx4 v[156:159], v[44:45], off nt
	s_waitcnt lgkmcnt(14)
	v_mov_b32_e32 v38, v63
	v_mov_b32_e32 v44, v71
	s_waitcnt lgkmcnt(13)
	v_mov_b32_e32 v160, v79
	s_waitcnt lgkmcnt(11)
	v_mov_b32_e32 v162, v87
	s_waitcnt lgkmcnt(9)
	v_mov_b32_e32 v164, v95
	s_waitcnt lgkmcnt(7)
	v_mov_b32_e32 v166, v103
	s_waitcnt lgkmcnt(5)
	v_mov_b32_e32 v168, v111
	s_waitcnt lgkmcnt(3)
	v_mov_b32_e32 v170, v119
	s_waitcnt lgkmcnt(1)
	v_mov_b32_e32 v172, v127
	s_add_i32 s30, s30, 32
	v_mov_b32_e32 v174, v67
	v_mov_b32_e32 v176, v75
	v_mov_b32_e32 v178, v83
	v_mov_b32_e32 v180, v91
	v_mov_b32_e32 v182, v99
	v_mov_b32_e32 v184, v107
	v_mov_b32_e32 v186, v115
	v_mov_b32_e32 v188, v123
	s_waitcnt lgkmcnt(0)
	v_mov_b32_e32 v190, v131
	s_waitcnt vmcnt(15)
	v_pk_fma_f32 v[20:21], v[60:61], v[192:193], v[20:21] op_sel_hi:[0,1,1]
	v_pk_fma_f32 v[22:23], v[60:61], v[194:195], v[22:23] op_sel_hi:[0,1,1]
	v_pk_fma_f32 v[32:33], v[192:193], v[68:69], v[32:33] op_sel_hi:[1,0,1]
	v_pk_fma_f32 v[34:35], v[194:195], v[68:69], v[34:35] op_sel_hi:[1,0,1]
	v_pk_fma_f32 v[28:29], v[192:193], v[76:77], v[28:29] op_sel_hi:[1,0,1]
	v_pk_fma_f32 v[30:31], v[194:195], v[76:77], v[30:31] op_sel_hi:[1,0,1]
	v_pk_fma_f32 v[24:25], v[192:193], v[84:85], v[24:25] op_sel_hi:[1,0,1]
	v_pk_fma_f32 v[26:27], v[194:195], v[84:85], v[26:27] op_sel_hi:[1,0,1]
	v_pk_fma_f32 v[16:17], v[192:193], v[92:93], v[16:17] op_sel_hi:[1,0,1]
	v_pk_fma_f32 v[18:19], v[194:195], v[92:93], v[18:19] op_sel_hi:[1,0,1]
	v_pk_fma_f32 v[12:13], v[192:193], v[100:101], v[12:13] op_sel_hi:[1,0,1]
	v_pk_fma_f32 v[14:15], v[194:195], v[100:101], v[14:15] op_sel_hi:[1,0,1]
	v_pk_fma_f32 v[8:9], v[192:193], v[108:109], v[8:9] op_sel_hi:[1,0,1]
	v_pk_fma_f32 v[10:11], v[194:195], v[108:109], v[10:11] op_sel_hi:[1,0,1]
	v_pk_fma_f32 v[4:5], v[192:193], v[116:117], v[4:5] op_sel_hi:[1,0,1]
	v_pk_fma_f32 v[6:7], v[194:195], v[116:117], v[6:7] op_sel_hi:[1,0,1]
	v_pk_fma_f32 v[0:1], v[192:193], v[124:125], v[0:1] op_sel_hi:[1,0,1]
	v_pk_fma_f32 v[2:3], v[194:195], v[124:125], v[2:3] op_sel_hi:[1,0,1]
	s_waitcnt vmcnt(14)
	v_pk_fma_f32 v[20:21], v[60:61], v[196:197], v[20:21] op_sel:[1,0,0]
	v_pk_fma_f32 v[22:23], v[60:61], v[198:199], v[22:23] op_sel:[1,0,0]
	v_pk_fma_f32 v[32:33], v[196:197], v[68:69], v[32:33] op_sel:[0,1,0]
	v_pk_fma_f32 v[34:35], v[198:199], v[68:69], v[34:35] op_sel:[0,1,0]
	v_pk_fma_f32 v[28:29], v[196:197], v[76:77], v[28:29] op_sel:[0,1,0]
	v_pk_fma_f32 v[30:31], v[198:199], v[76:77], v[30:31] op_sel:[0,1,0]
	v_pk_fma_f32 v[24:25], v[196:197], v[84:85], v[24:25] op_sel:[0,1,0]
	v_pk_fma_f32 v[26:27], v[198:199], v[84:85], v[26:27] op_sel:[0,1,0]
	v_pk_fma_f32 v[16:17], v[196:197], v[92:93], v[16:17] op_sel:[0,1,0]
	v_pk_fma_f32 v[18:19], v[198:199], v[92:93], v[18:19] op_sel:[0,1,0]
	v_pk_fma_f32 v[12:13], v[196:197], v[100:101], v[12:13] op_sel:[0,1,0]
	v_pk_fma_f32 v[14:15], v[198:199], v[100:101], v[14:15] op_sel:[0,1,0]
	v_pk_fma_f32 v[8:9], v[196:197], v[108:109], v[8:9] op_sel:[0,1,0]
	v_pk_fma_f32 v[10:11], v[198:199], v[108:109], v[10:11] op_sel:[0,1,0]
	v_pk_fma_f32 v[4:5], v[196:197], v[116:117], v[4:5] op_sel:[0,1,0]
	v_pk_fma_f32 v[6:7], v[198:199], v[116:117], v[6:7] op_sel:[0,1,0]
	v_pk_fma_f32 v[0:1], v[196:197], v[124:125], v[0:1] op_sel:[0,1,0]
	v_pk_fma_f32 v[2:3], v[198:199], v[124:125], v[2:3] op_sel:[0,1,0]
	s_waitcnt vmcnt(13)
	v_pk_fma_f32 v[20:21], v[62:63], v[200:201], v[20:21] op_sel_hi:[0,1,1]
	v_pk_fma_f32 v[22:23], v[62:63], v[202:203], v[22:23] op_sel_hi:[0,1,1]
	v_pk_fma_f32 v[32:33], v[200:201], v[70:71], v[32:33] op_sel_hi:[1,0,1]
	v_pk_fma_f32 v[34:35], v[202:203], v[70:71], v[34:35] op_sel_hi:[1,0,1]
	v_pk_fma_f32 v[28:29], v[200:201], v[78:79], v[28:29] op_sel_hi:[1,0,1]
	v_pk_fma_f32 v[30:31], v[202:203], v[78:79], v[30:31] op_sel_hi:[1,0,1]
	v_pk_fma_f32 v[24:25], v[200:201], v[86:87], v[24:25] op_sel_hi:[1,0,1]
	v_pk_fma_f32 v[26:27], v[202:203], v[86:87], v[26:27] op_sel_hi:[1,0,1]
	v_pk_fma_f32 v[16:17], v[200:201], v[94:95], v[16:17] op_sel_hi:[1,0,1]
	v_pk_fma_f32 v[18:19], v[202:203], v[94:95], v[18:19] op_sel_hi:[1,0,1]
	v_pk_fma_f32 v[12:13], v[200:201], v[102:103], v[12:13] op_sel_hi:[1,0,1]
	v_pk_fma_f32 v[14:15], v[202:203], v[102:103], v[14:15] op_sel_hi:[1,0,1]
	v_pk_fma_f32 v[8:9], v[200:201], v[110:111], v[8:9] op_sel_hi:[1,0,1]
	v_pk_fma_f32 v[10:11], v[202:203], v[110:111], v[10:11] op_sel_hi:[1,0,1]
	v_pk_fma_f32 v[4:5], v[200:201], v[118:119], v[4:5] op_sel_hi:[1,0,1]
	v_pk_fma_f32 v[6:7], v[202:203], v[118:119], v[6:7] op_sel_hi:[1,0,1]
	v_pk_fma_f32 v[0:1], v[200:201], v[126:127], v[0:1] op_sel_hi:[1,0,1]
	v_pk_fma_f32 v[2:3], v[202:203], v[126:127], v[2:3] op_sel_hi:[1,0,1]
	s_waitcnt vmcnt(12)
	v_pk_fma_f32 v[20:21], v[38:39], v[204:205], v[20:21] op_sel_hi:[0,1,1]
	v_pk_fma_f32 v[22:23], v[38:39], v[206:207], v[22:23] op_sel_hi:[0,1,1]
	v_pk_fma_f32 v[32:33], v[204:205], v[44:45], v[32:33] op_sel_hi:[1,0,1]
	v_pk_fma_f32 v[34:35], v[206:207], v[44:45], v[34:35] op_sel_hi:[1,0,1]
	v_pk_fma_f32 v[28:29], v[204:205], v[160:161], v[28:29] op_sel_hi:[1,0,1]
	v_pk_fma_f32 v[30:31], v[206:207], v[160:161], v[30:31] op_sel_hi:[1,0,1]
	v_pk_fma_f32 v[24:25], v[204:205], v[162:163], v[24:25] op_sel_hi:[1,0,1]
	v_pk_fma_f32 v[26:27], v[206:207], v[162:163], v[26:27] op_sel_hi:[1,0,1]
	v_pk_fma_f32 v[16:17], v[204:205], v[164:165], v[16:17] op_sel_hi:[1,0,1]
	v_pk_fma_f32 v[18:19], v[206:207], v[164:165], v[18:19] op_sel_hi:[1,0,1]
	v_pk_fma_f32 v[12:13], v[204:205], v[166:167], v[12:13] op_sel_hi:[1,0,1]
	v_pk_fma_f32 v[14:15], v[206:207], v[166:167], v[14:15] op_sel_hi:[1,0,1]
	v_pk_fma_f32 v[8:9], v[204:205], v[168:169], v[8:9] op_sel_hi:[1,0,1]
	v_pk_fma_f32 v[10:11], v[206:207], v[168:169], v[10:11] op_sel_hi:[1,0,1]
	v_pk_fma_f32 v[4:5], v[204:205], v[170:171], v[4:5] op_sel_hi:[1,0,1]
	v_pk_fma_f32 v[6:7], v[206:207], v[170:171], v[6:7] op_sel_hi:[1,0,1]
	v_pk_fma_f32 v[0:1], v[204:205], v[172:173], v[0:1] op_sel_hi:[1,0,1]
	v_pk_fma_f32 v[2:3], v[206:207], v[172:173], v[2:3] op_sel_hi:[1,0,1]
	s_waitcnt vmcnt(11)
	v_pk_fma_f32 v[20:21], v[64:65], v[208:209], v[20:21] op_sel_hi:[0,1,1]
	v_pk_fma_f32 v[22:23], v[64:65], v[210:211], v[22:23] op_sel_hi:[0,1,1]
	v_pk_fma_f32 v[32:33], v[208:209], v[72:73], v[32:33] op_sel_hi:[1,0,1]
	v_pk_fma_f32 v[34:35], v[210:211], v[72:73], v[34:35] op_sel_hi:[1,0,1]
	v_pk_fma_f32 v[28:29], v[208:209], v[80:81], v[28:29] op_sel_hi:[1,0,1]
	v_pk_fma_f32 v[30:31], v[210:211], v[80:81], v[30:31] op_sel_hi:[1,0,1]
	v_pk_fma_f32 v[24:25], v[208:209], v[88:89], v[24:25] op_sel_hi:[1,0,1]
	v_pk_fma_f32 v[26:27], v[210:211], v[88:89], v[26:27] op_sel_hi:[1,0,1]
	v_pk_fma_f32 v[16:17], v[208:209], v[96:97], v[16:17] op_sel_hi:[1,0,1]
	v_pk_fma_f32 v[18:19], v[210:211], v[96:97], v[18:19] op_sel_hi:[1,0,1]
	v_pk_fma_f32 v[12:13], v[208:209], v[104:105], v[12:13] op_sel_hi:[1,0,1]
	v_pk_fma_f32 v[14:15], v[210:211], v[104:105], v[14:15] op_sel_hi:[1,0,1]
	v_pk_fma_f32 v[8:9], v[208:209], v[112:113], v[8:9] op_sel_hi:[1,0,1]
	v_pk_fma_f32 v[10:11], v[210:211], v[112:113], v[10:11] op_sel_hi:[1,0,1]
	v_pk_fma_f32 v[4:5], v[208:209], v[120:121], v[4:5] op_sel_hi:[1,0,1]
	v_pk_fma_f32 v[6:7], v[210:211], v[120:121], v[6:7] op_sel_hi:[1,0,1]
	v_pk_fma_f32 v[0:1], v[208:209], v[128:129], v[0:1] op_sel_hi:[1,0,1]
	v_pk_fma_f32 v[2:3], v[210:211], v[128:129], v[2:3] op_sel_hi:[1,0,1]
	s_waitcnt vmcnt(10)
	v_pk_fma_f32 v[20:21], v[64:65], v[212:213], v[20:21] op_sel:[1,0,0]
	v_pk_fma_f32 v[22:23], v[64:65], v[214:215], v[22:23] op_sel:[1,0,0]
	v_pk_fma_f32 v[32:33], v[212:213], v[72:73], v[32:33] op_sel:[0,1,0]
	v_pk_fma_f32 v[34:35], v[214:215], v[72:73], v[34:35] op_sel:[0,1,0]
	v_pk_fma_f32 v[28:29], v[212:213], v[80:81], v[28:29] op_sel:[0,1,0]
	v_pk_fma_f32 v[30:31], v[214:215], v[80:81], v[30:31] op_sel:[0,1,0]
	v_pk_fma_f32 v[24:25], v[212:213], v[88:89], v[24:25] op_sel:[0,1,0]
	v_pk_fma_f32 v[26:27], v[214:215], v[88:89], v[26:27] op_sel:[0,1,0]
	v_pk_fma_f32 v[16:17], v[212:213], v[96:97], v[16:17] op_sel:[0,1,0]
	v_pk_fma_f32 v[18:19], v[214:215], v[96:97], v[18:19] op_sel:[0,1,0]
	v_pk_fma_f32 v[12:13], v[212:213], v[104:105], v[12:13] op_sel:[0,1,0]
	v_pk_fma_f32 v[14:15], v[214:215], v[104:105], v[14:15] op_sel:[0,1,0]
	v_pk_fma_f32 v[8:9], v[212:213], v[112:113], v[8:9] op_sel:[0,1,0]
	v_pk_fma_f32 v[10:11], v[214:215], v[112:113], v[10:11] op_sel:[0,1,0]
	v_pk_fma_f32 v[4:5], v[212:213], v[120:121], v[4:5] op_sel:[0,1,0]
	v_pk_fma_f32 v[6:7], v[214:215], v[120:121], v[6:7] op_sel:[0,1,0]
	v_pk_fma_f32 v[0:1], v[212:213], v[128:129], v[0:1] op_sel:[0,1,0]
	v_pk_fma_f32 v[2:3], v[214:215], v[128:129], v[2:3] op_sel:[0,1,0]
	s_waitcnt vmcnt(9)
	v_pk_fma_f32 v[20:21], v[66:67], v[216:217], v[20:21] op_sel_hi:[0,1,1]
	v_pk_fma_f32 v[22:23], v[66:67], v[218:219], v[22:23] op_sel_hi:[0,1,1]
	v_pk_fma_f32 v[32:33], v[216:217], v[74:75], v[32:33] op_sel_hi:[1,0,1]
	v_pk_fma_f32 v[34:35], v[218:219], v[74:75], v[34:35] op_sel_hi:[1,0,1]
	v_pk_fma_f32 v[28:29], v[216:217], v[82:83], v[28:29] op_sel_hi:[1,0,1]
	v_pk_fma_f32 v[30:31], v[218:219], v[82:83], v[30:31] op_sel_hi:[1,0,1]
	v_pk_fma_f32 v[24:25], v[216:217], v[90:91], v[24:25] op_sel_hi:[1,0,1]
	v_pk_fma_f32 v[26:27], v[218:219], v[90:91], v[26:27] op_sel_hi:[1,0,1]
	v_pk_fma_f32 v[16:17], v[216:217], v[98:99], v[16:17] op_sel_hi:[1,0,1]
	v_pk_fma_f32 v[18:19], v[218:219], v[98:99], v[18:19] op_sel_hi:[1,0,1]
	v_pk_fma_f32 v[12:13], v[216:217], v[106:107], v[12:13] op_sel_hi:[1,0,1]
	v_pk_fma_f32 v[14:15], v[218:219], v[106:107], v[14:15] op_sel_hi:[1,0,1]
	v_pk_fma_f32 v[8:9], v[216:217], v[114:115], v[8:9] op_sel_hi:[1,0,1]
	v_pk_fma_f32 v[10:11], v[218:219], v[114:115], v[10:11] op_sel_hi:[1,0,1]
	v_pk_fma_f32 v[4:5], v[216:217], v[122:123], v[4:5] op_sel_hi:[1,0,1]
	v_pk_fma_f32 v[6:7], v[218:219], v[122:123], v[6:7] op_sel_hi:[1,0,1]
	v_pk_fma_f32 v[0:1], v[216:217], v[130:131], v[0:1] op_sel_hi:[1,0,1]
	v_pk_fma_f32 v[2:3], v[218:219], v[130:131], v[2:3] op_sel_hi:[1,0,1]
	s_waitcnt vmcnt(8)
	v_pk_fma_f32 v[20:21], v[174:175], v[220:221], v[20:21] op_sel_hi:[0,1,1]
	v_pk_fma_f32 v[22:23], v[174:175], v[222:223], v[22:23] op_sel_hi:[0,1,1]
	v_pk_fma_f32 v[32:33], v[220:221], v[176:177], v[32:33] op_sel_hi:[1,0,1]
	v_pk_fma_f32 v[34:35], v[222:223], v[176:177], v[34:35] op_sel_hi:[1,0,1]
	v_pk_fma_f32 v[28:29], v[220:221], v[178:179], v[28:29] op_sel_hi:[1,0,1]
	v_pk_fma_f32 v[30:31], v[222:223], v[178:179], v[30:31] op_sel_hi:[1,0,1]
	v_pk_fma_f32 v[24:25], v[220:221], v[180:181], v[24:25] op_sel_hi:[1,0,1]
	v_pk_fma_f32 v[26:27], v[222:223], v[180:181], v[26:27] op_sel_hi:[1,0,1]
	v_pk_fma_f32 v[16:17], v[220:221], v[182:183], v[16:17] op_sel_hi:[1,0,1]
	v_pk_fma_f32 v[18:19], v[222:223], v[182:183], v[18:19] op_sel_hi:[1,0,1]
	v_pk_fma_f32 v[12:13], v[220:221], v[184:185], v[12:13] op_sel_hi:[1,0,1]
	v_pk_fma_f32 v[14:15], v[222:223], v[184:185], v[14:15] op_sel_hi:[1,0,1]
	v_pk_fma_f32 v[8:9], v[220:221], v[186:187], v[8:9] op_sel_hi:[1,0,1]
	v_pk_fma_f32 v[10:11], v[222:223], v[186:187], v[10:11] op_sel_hi:[1,0,1]
	v_pk_fma_f32 v[4:5], v[220:221], v[188:189], v[4:5] op_sel_hi:[1,0,1]
	v_pk_fma_f32 v[6:7], v[222:223], v[188:189], v[6:7] op_sel_hi:[1,0,1]
	v_pk_fma_f32 v[0:1], v[220:221], v[190:191], v[0:1] op_sel_hi:[1,0,1]
	v_pk_fma_f32 v[2:3], v[222:223], v[190:191], v[2:3] op_sel_hi:[1,0,1]
	s_cmp_lg_u32 s28, 0x240000
	s_cbranch_scc1 .LBB0_28
	s_add_u32 s28, s28, 0x60000
	s_addc_u32 s29, s29, 0
	v_lshl_add_u64 v[44:45], v[42:43], 0, s[28:29]
	v_add_co_u32_e32 v196, vcc, s94, v44
	s_mov_b32 s31, 0x18000
	s_nop 0
	v_addc_co_u32_e32 v197, vcc, 0, v45, vcc
	v_add_co_u32_e32 v200, vcc, s31, v44
	s_mov_b32 s64, 0x24000
	s_nop 0
	v_addc_co_u32_e32 v201, vcc, 0, v45, vcc
	v_add_co_u32_e32 v204, vcc, s64, v44
	s_mov_b32 s65, 0x30000
	s_nop 0
	v_addc_co_u32_e32 v205, vcc, 0, v45, vcc
	global_load_dwordx4 v[192:195], v[44:45], off nt
	v_add_co_u32_e32 v208, vcc, s65, v44
	s_mov_b32 s67, 0x3c000
	s_nop 0
	v_addc_co_u32_e32 v209, vcc, 0, v45, vcc
	v_add_co_u32_e32 v212, vcc, s67, v44
	s_mov_b32 s73, 0x48000
	s_nop 0
	v_addc_co_u32_e32 v213, vcc, 0, v45, vcc
	v_add_co_u32_e32 v216, vcc, s73, v44
	v_mov_b32_e32 v38, s30
	s_nop 0
	v_addc_co_u32_e32 v217, vcc, 0, v45, vcc
	v_add_co_u32_e32 v44, vcc, s95, v44
	ds_read_b128 v[60:63], v38
	ds_read_b128 v[64:67], v38 offset:16
	ds_read_b128 v[68:71], v38 offset:2048
	ds_read_b128 v[72:75], v38 offset:2064
	ds_read_b128 v[76:79], v38 offset:4096
	ds_read_b128 v[80:83], v38 offset:4112
	ds_read_b128 v[84:87], v38 offset:6144
	ds_read_b128 v[88:91], v38 offset:6160
	ds_read_b128 v[92:95], v38 offset:8192
	ds_read_b128 v[96:99], v38 offset:8208
	ds_read_b128 v[100:103], v38 offset:10240
	ds_read_b128 v[104:107], v38 offset:10256
	ds_read_b128 v[108:111], v38 offset:12288
	ds_read_b128 v[112:115], v38 offset:12304
	ds_read_b128 v[116:119], v38 offset:14336
	ds_read_b128 v[120:123], v38 offset:14352
	ds_read_b128 v[124:127], v38 offset:16384
	ds_read_b128 v[128:131], v38 offset:16400
	v_addc_co_u32_e32 v45, vcc, 0, v45, vcc
	global_load_dwordx4 v[196:199], v[196:197], off nt
	s_nop 0
	global_load_dwordx4 v[200:203], v[200:201], off nt
	s_nop 0
	global_load_dwordx4 v[204:207], v[204:205], off nt
	s_nop 0
	global_load_dwordx4 v[208:211], v[208:209], off nt
	s_nop 0
	global_load_dwordx4 v[212:215], v[212:213], off nt
	s_nop 0
	global_load_dwordx4 v[216:219], v[216:217], off nt
	s_nop 0
	global_load_dwordx4 v[220:223], v[44:45], off nt
	s_waitcnt lgkmcnt(14)
	v_mov_b32_e32 v38, v63
	v_mov_b32_e32 v44, v71
	s_waitcnt lgkmcnt(13)
	v_mov_b32_e32 v160, v79
	s_waitcnt lgkmcnt(11)
	v_mov_b32_e32 v162, v87
	s_waitcnt lgkmcnt(9)
	v_mov_b32_e32 v164, v95
	s_waitcnt lgkmcnt(7)
	v_mov_b32_e32 v166, v103
	s_waitcnt lgkmcnt(5)
	v_mov_b32_e32 v168, v111
	s_waitcnt lgkmcnt(3)
	v_mov_b32_e32 v170, v119
	s_waitcnt lgkmcnt(1)
	v_mov_b32_e32 v172, v127
	s_add_i32 s30, s30, 32
	v_mov_b32_e32 v174, v67
	v_mov_b32_e32 v176, v75
	v_mov_b32_e32 v178, v83
	v_mov_b32_e32 v180, v91
	v_mov_b32_e32 v182, v99
	v_mov_b32_e32 v184, v107
	v_mov_b32_e32 v186, v115
	v_mov_b32_e32 v188, v123
	s_waitcnt lgkmcnt(0)
	v_mov_b32_e32 v190, v131
	s_waitcnt vmcnt(15)
	v_pk_fma_f32 v[20:21], v[60:61], v[56:57], v[20:21] op_sel_hi:[0,1,1]
	v_pk_fma_f32 v[22:23], v[60:61], v[58:59], v[22:23] op_sel_hi:[0,1,1]
	v_pk_fma_f32 v[32:33], v[56:57], v[68:69], v[32:33] op_sel_hi:[1,0,1]
	v_pk_fma_f32 v[34:35], v[58:59], v[68:69], v[34:35] op_sel_hi:[1,0,1]
	v_pk_fma_f32 v[28:29], v[56:57], v[76:77], v[28:29] op_sel_hi:[1,0,1]
	v_pk_fma_f32 v[30:31], v[58:59], v[76:77], v[30:31] op_sel_hi:[1,0,1]
	v_pk_fma_f32 v[24:25], v[56:57], v[84:85], v[24:25] op_sel_hi:[1,0,1]
	v_pk_fma_f32 v[26:27], v[58:59], v[84:85], v[26:27] op_sel_hi:[1,0,1]
	v_pk_fma_f32 v[16:17], v[56:57], v[92:93], v[16:17] op_sel_hi:[1,0,1]
	v_pk_fma_f32 v[18:19], v[58:59], v[92:93], v[18:19] op_sel_hi:[1,0,1]
	v_pk_fma_f32 v[12:13], v[56:57], v[100:101], v[12:13] op_sel_hi:[1,0,1]
	v_pk_fma_f32 v[14:15], v[58:59], v[100:101], v[14:15] op_sel_hi:[1,0,1]
	v_pk_fma_f32 v[8:9], v[56:57], v[108:109], v[8:9] op_sel_hi:[1,0,1]
	v_pk_fma_f32 v[10:11], v[58:59], v[108:109], v[10:11] op_sel_hi:[1,0,1]
	v_pk_fma_f32 v[4:5], v[56:57], v[116:117], v[4:5] op_sel_hi:[1,0,1]
	v_pk_fma_f32 v[6:7], v[58:59], v[116:117], v[6:7] op_sel_hi:[1,0,1]
	v_pk_fma_f32 v[0:1], v[56:57], v[124:125], v[0:1] op_sel_hi:[1,0,1]
	v_pk_fma_f32 v[2:3], v[58:59], v[124:125], v[2:3] op_sel_hi:[1,0,1]
	s_waitcnt vmcnt(14)
	v_pk_fma_f32 v[20:21], v[60:61], v[132:133], v[20:21] op_sel:[1,0,0]
	v_pk_fma_f32 v[22:23], v[60:61], v[134:135], v[22:23] op_sel:[1,0,0]
	v_pk_fma_f32 v[32:33], v[132:133], v[68:69], v[32:33] op_sel:[0,1,0]
	v_pk_fma_f32 v[34:35], v[134:135], v[68:69], v[34:35] op_sel:[0,1,0]
	v_pk_fma_f32 v[28:29], v[132:133], v[76:77], v[28:29] op_sel:[0,1,0]
	v_pk_fma_f32 v[30:31], v[134:135], v[76:77], v[30:31] op_sel:[0,1,0]
	v_pk_fma_f32 v[24:25], v[132:133], v[84:85], v[24:25] op_sel:[0,1,0]
	v_pk_fma_f32 v[26:27], v[134:135], v[84:85], v[26:27] op_sel:[0,1,0]
	v_pk_fma_f32 v[16:17], v[132:133], v[92:93], v[16:17] op_sel:[0,1,0]
	v_pk_fma_f32 v[18:19], v[134:135], v[92:93], v[18:19] op_sel:[0,1,0]
	v_pk_fma_f32 v[12:13], v[132:133], v[100:101], v[12:13] op_sel:[0,1,0]
	v_pk_fma_f32 v[14:15], v[134:135], v[100:101], v[14:15] op_sel:[0,1,0]
	v_pk_fma_f32 v[8:9], v[132:133], v[108:109], v[8:9] op_sel:[0,1,0]
	v_pk_fma_f32 v[10:11], v[134:135], v[108:109], v[10:11] op_sel:[0,1,0]
	v_pk_fma_f32 v[4:5], v[132:133], v[116:117], v[4:5] op_sel:[0,1,0]
	v_pk_fma_f32 v[6:7], v[134:135], v[116:117], v[6:7] op_sel:[0,1,0]
	v_pk_fma_f32 v[0:1], v[132:133], v[124:125], v[0:1] op_sel:[0,1,0]
	v_pk_fma_f32 v[2:3], v[134:135], v[124:125], v[2:3] op_sel:[0,1,0]
	s_waitcnt vmcnt(13)
	v_pk_fma_f32 v[20:21], v[62:63], v[136:137], v[20:21] op_sel_hi:[0,1,1]
	v_pk_fma_f32 v[22:23], v[62:63], v[138:139], v[22:23] op_sel_hi:[0,1,1]
	v_pk_fma_f32 v[32:33], v[136:137], v[70:71], v[32:33] op_sel_hi:[1,0,1]
	v_pk_fma_f32 v[34:35], v[138:139], v[70:71], v[34:35] op_sel_hi:[1,0,1]
	v_pk_fma_f32 v[28:29], v[136:137], v[78:79], v[28:29] op_sel_hi:[1,0,1]
	v_pk_fma_f32 v[30:31], v[138:139], v[78:79], v[30:31] op_sel_hi:[1,0,1]
	v_pk_fma_f32 v[24:25], v[136:137], v[86:87], v[24:25] op_sel_hi:[1,0,1]
	v_pk_fma_f32 v[26:27], v[138:139], v[86:87], v[26:27] op_sel_hi:[1,0,1]
	v_pk_fma_f32 v[16:17], v[136:137], v[94:95], v[16:17] op_sel_hi:[1,0,1]
	v_pk_fma_f32 v[18:19], v[138:139], v[94:95], v[18:19] op_sel_hi:[1,0,1]
	v_pk_fma_f32 v[12:13], v[136:137], v[102:103], v[12:13] op_sel_hi:[1,0,1]
	v_pk_fma_f32 v[14:15], v[138:139], v[102:103], v[14:15] op_sel_hi:[1,0,1]
	v_pk_fma_f32 v[8:9], v[136:137], v[110:111], v[8:9] op_sel_hi:[1,0,1]
	v_pk_fma_f32 v[10:11], v[138:139], v[110:111], v[10:11] op_sel_hi:[1,0,1]
	v_pk_fma_f32 v[4:5], v[136:137], v[118:119], v[4:5] op_sel_hi:[1,0,1]
	v_pk_fma_f32 v[6:7], v[138:139], v[118:119], v[6:7] op_sel_hi:[1,0,1]
	v_pk_fma_f32 v[0:1], v[136:137], v[126:127], v[0:1] op_sel_hi:[1,0,1]
	v_pk_fma_f32 v[2:3], v[138:139], v[126:127], v[2:3] op_sel_hi:[1,0,1]
	s_waitcnt vmcnt(12)
	v_pk_fma_f32 v[20:21], v[38:39], v[140:141], v[20:21] op_sel_hi:[0,1,1]
	v_pk_fma_f32 v[22:23], v[38:39], v[142:143], v[22:23] op_sel_hi:[0,1,1]
	v_pk_fma_f32 v[32:33], v[140:141], v[44:45], v[32:33] op_sel_hi:[1,0,1]
	v_pk_fma_f32 v[34:35], v[142:143], v[44:45], v[34:35] op_sel_hi:[1,0,1]
	v_pk_fma_f32 v[28:29], v[140:141], v[160:161], v[28:29] op_sel_hi:[1,0,1]
	v_pk_fma_f32 v[30:31], v[142:143], v[160:161], v[30:31] op_sel_hi:[1,0,1]
	v_pk_fma_f32 v[24:25], v[140:141], v[162:163], v[24:25] op_sel_hi:[1,0,1]
	v_pk_fma_f32 v[26:27], v[142:143], v[162:163], v[26:27] op_sel_hi:[1,0,1]
	v_pk_fma_f32 v[16:17], v[140:141], v[164:165], v[16:17] op_sel_hi:[1,0,1]
	v_pk_fma_f32 v[18:19], v[142:143], v[164:165], v[18:19] op_sel_hi:[1,0,1]
	v_pk_fma_f32 v[12:13], v[140:141], v[166:167], v[12:13] op_sel_hi:[1,0,1]
	v_pk_fma_f32 v[14:15], v[142:143], v[166:167], v[14:15] op_sel_hi:[1,0,1]
	v_pk_fma_f32 v[8:9], v[140:141], v[168:169], v[8:9] op_sel_hi:[1,0,1]
	v_pk_fma_f32 v[10:11], v[142:143], v[168:169], v[10:11] op_sel_hi:[1,0,1]
	v_pk_fma_f32 v[4:5], v[140:141], v[170:171], v[4:5] op_sel_hi:[1,0,1]
	v_pk_fma_f32 v[6:7], v[142:143], v[170:171], v[6:7] op_sel_hi:[1,0,1]
	v_pk_fma_f32 v[0:1], v[140:141], v[172:173], v[0:1] op_sel_hi:[1,0,1]
	v_pk_fma_f32 v[2:3], v[142:143], v[172:173], v[2:3] op_sel_hi:[1,0,1]
	s_waitcnt vmcnt(11)
	v_pk_fma_f32 v[20:21], v[64:65], v[144:145], v[20:21] op_sel_hi:[0,1,1]
	v_pk_fma_f32 v[22:23], v[64:65], v[146:147], v[22:23] op_sel_hi:[0,1,1]
	v_pk_fma_f32 v[32:33], v[144:145], v[72:73], v[32:33] op_sel_hi:[1,0,1]
	v_pk_fma_f32 v[34:35], v[146:147], v[72:73], v[34:35] op_sel_hi:[1,0,1]
	v_pk_fma_f32 v[28:29], v[144:145], v[80:81], v[28:29] op_sel_hi:[1,0,1]
	v_pk_fma_f32 v[30:31], v[146:147], v[80:81], v[30:31] op_sel_hi:[1,0,1]
	v_pk_fma_f32 v[24:25], v[144:145], v[88:89], v[24:25] op_sel_hi:[1,0,1]
	v_pk_fma_f32 v[26:27], v[146:147], v[88:89], v[26:27] op_sel_hi:[1,0,1]
	v_pk_fma_f32 v[16:17], v[144:145], v[96:97], v[16:17] op_sel_hi:[1,0,1]
	v_pk_fma_f32 v[18:19], v[146:147], v[96:97], v[18:19] op_sel_hi:[1,0,1]
	v_pk_fma_f32 v[12:13], v[144:145], v[104:105], v[12:13] op_sel_hi:[1,0,1]
	v_pk_fma_f32 v[14:15], v[146:147], v[104:105], v[14:15] op_sel_hi:[1,0,1]
	v_pk_fma_f32 v[8:9], v[144:145], v[112:113], v[8:9] op_sel_hi:[1,0,1]
	v_pk_fma_f32 v[10:11], v[146:147], v[112:113], v[10:11] op_sel_hi:[1,0,1]
	v_pk_fma_f32 v[4:5], v[144:145], v[120:121], v[4:5] op_sel_hi:[1,0,1]
	v_pk_fma_f32 v[6:7], v[146:147], v[120:121], v[6:7] op_sel_hi:[1,0,1]
	v_pk_fma_f32 v[0:1], v[144:145], v[128:129], v[0:1] op_sel_hi:[1,0,1]
	v_pk_fma_f32 v[2:3], v[146:147], v[128:129], v[2:3] op_sel_hi:[1,0,1]
	s_waitcnt vmcnt(10)
	v_pk_fma_f32 v[20:21], v[64:65], v[148:149], v[20:21] op_sel:[1,0,0]
	v_pk_fma_f32 v[22:23], v[64:65], v[150:151], v[22:23] op_sel:[1,0,0]
	v_pk_fma_f32 v[32:33], v[148:149], v[72:73], v[32:33] op_sel:[0,1,0]
	v_pk_fma_f32 v[34:35], v[150:151], v[72:73], v[34:35] op_sel:[0,1,0]
	v_pk_fma_f32 v[28:29], v[148:149], v[80:81], v[28:29] op_sel:[0,1,0]
	v_pk_fma_f32 v[30:31], v[150:151], v[80:81], v[30:31] op_sel:[0,1,0]
	v_pk_fma_f32 v[24:25], v[148:149], v[88:89], v[24:25] op_sel:[0,1,0]
	v_pk_fma_f32 v[26:27], v[150:151], v[88:89], v[26:27] op_sel:[0,1,0]
	v_pk_fma_f32 v[16:17], v[148:149], v[96:97], v[16:17] op_sel:[0,1,0]
	v_pk_fma_f32 v[18:19], v[150:151], v[96:97], v[18:19] op_sel:[0,1,0]
	v_pk_fma_f32 v[12:13], v[148:149], v[104:105], v[12:13] op_sel:[0,1,0]
	v_pk_fma_f32 v[14:15], v[150:151], v[104:105], v[14:15] op_sel:[0,1,0]
	v_pk_fma_f32 v[8:9], v[148:149], v[112:113], v[8:9] op_sel:[0,1,0]
	v_pk_fma_f32 v[10:11], v[150:151], v[112:113], v[10:11] op_sel:[0,1,0]
	v_pk_fma_f32 v[4:5], v[148:149], v[120:121], v[4:5] op_sel:[0,1,0]
	v_pk_fma_f32 v[6:7], v[150:151], v[120:121], v[6:7] op_sel:[0,1,0]
	v_pk_fma_f32 v[0:1], v[148:149], v[128:129], v[0:1] op_sel:[0,1,0]
	v_pk_fma_f32 v[2:3], v[150:151], v[128:129], v[2:3] op_sel:[0,1,0]
	s_waitcnt vmcnt(9)
	v_pk_fma_f32 v[20:21], v[66:67], v[152:153], v[20:21] op_sel_hi:[0,1,1]
	v_pk_fma_f32 v[22:23], v[66:67], v[154:155], v[22:23] op_sel_hi:[0,1,1]
	v_pk_fma_f32 v[32:33], v[152:153], v[74:75], v[32:33] op_sel_hi:[1,0,1]
	v_pk_fma_f32 v[34:35], v[154:155], v[74:75], v[34:35] op_sel_hi:[1,0,1]
	v_pk_fma_f32 v[28:29], v[152:153], v[82:83], v[28:29] op_sel_hi:[1,0,1]
	v_pk_fma_f32 v[30:31], v[154:155], v[82:83], v[30:31] op_sel_hi:[1,0,1]
	v_pk_fma_f32 v[24:25], v[152:153], v[90:91], v[24:25] op_sel_hi:[1,0,1]
	v_pk_fma_f32 v[26:27], v[154:155], v[90:91], v[26:27] op_sel_hi:[1,0,1]
	v_pk_fma_f32 v[16:17], v[152:153], v[98:99], v[16:17] op_sel_hi:[1,0,1]
	v_pk_fma_f32 v[18:19], v[154:155], v[98:99], v[18:19] op_sel_hi:[1,0,1]
	v_pk_fma_f32 v[12:13], v[152:153], v[106:107], v[12:13] op_sel_hi:[1,0,1]
	v_pk_fma_f32 v[14:15], v[154:155], v[106:107], v[14:15] op_sel_hi:[1,0,1]
	v_pk_fma_f32 v[8:9], v[152:153], v[114:115], v[8:9] op_sel_hi:[1,0,1]
	v_pk_fma_f32 v[10:11], v[154:155], v[114:115], v[10:11] op_sel_hi:[1,0,1]
	v_pk_fma_f32 v[4:5], v[152:153], v[122:123], v[4:5] op_sel_hi:[1,0,1]
	v_pk_fma_f32 v[6:7], v[154:155], v[122:123], v[6:7] op_sel_hi:[1,0,1]
	v_pk_fma_f32 v[0:1], v[152:153], v[130:131], v[0:1] op_sel_hi:[1,0,1]
	v_pk_fma_f32 v[2:3], v[154:155], v[130:131], v[2:3] op_sel_hi:[1,0,1]
	s_waitcnt vmcnt(8)
	v_pk_fma_f32 v[20:21], v[174:175], v[156:157], v[20:21] op_sel_hi:[0,1,1]
	v_pk_fma_f32 v[22:23], v[174:175], v[158:159], v[22:23] op_sel_hi:[0,1,1]
	v_pk_fma_f32 v[32:33], v[156:157], v[176:177], v[32:33] op_sel_hi:[1,0,1]
	v_pk_fma_f32 v[34:35], v[158:159], v[176:177], v[34:35] op_sel_hi:[1,0,1]
	v_pk_fma_f32 v[28:29], v[156:157], v[178:179], v[28:29] op_sel_hi:[1,0,1]
	v_pk_fma_f32 v[30:31], v[158:159], v[178:179], v[30:31] op_sel_hi:[1,0,1]
	v_pk_fma_f32 v[24:25], v[156:157], v[180:181], v[24:25] op_sel_hi:[1,0,1]
	v_pk_fma_f32 v[26:27], v[158:159], v[180:181], v[26:27] op_sel_hi:[1,0,1]
	v_pk_fma_f32 v[16:17], v[156:157], v[182:183], v[16:17] op_sel_hi:[1,0,1]
	v_pk_fma_f32 v[18:19], v[158:159], v[182:183], v[18:19] op_sel_hi:[1,0,1]
	v_pk_fma_f32 v[12:13], v[156:157], v[184:185], v[12:13] op_sel_hi:[1,0,1]
	v_pk_fma_f32 v[14:15], v[158:159], v[184:185], v[14:15] op_sel_hi:[1,0,1]
	v_pk_fma_f32 v[8:9], v[156:157], v[186:187], v[8:9] op_sel_hi:[1,0,1]
	v_pk_fma_f32 v[10:11], v[158:159], v[186:187], v[10:11] op_sel_hi:[1,0,1]
	v_pk_fma_f32 v[4:5], v[156:157], v[188:189], v[4:5] op_sel_hi:[1,0,1]
	v_pk_fma_f32 v[6:7], v[158:159], v[188:189], v[6:7] op_sel_hi:[1,0,1]
	v_pk_fma_f32 v[0:1], v[156:157], v[190:191], v[0:1] op_sel_hi:[1,0,1]
	v_pk_fma_f32 v[2:3], v[158:159], v[190:191], v[2:3] op_sel_hi:[1,0,1]
	v_mov_b32_e32 v38, s30
	ds_read_b128 v[60:63], v38
	ds_read_b128 v[64:67], v38 offset:16
	ds_read_b128 v[68:71], v38 offset:2048
	ds_read_b128 v[72:75], v38 offset:2064
	ds_read_b128 v[76:79], v38 offset:4096
	ds_read_b128 v[80:83], v38 offset:4112
	ds_read_b128 v[84:87], v38 offset:6144
	ds_read_b128 v[88:91], v38 offset:6160
	ds_read_b128 v[92:95], v38 offset:8192
	ds_read_b128 v[96:99], v38 offset:8208
	ds_read_b128 v[100:103], v38 offset:10240
	ds_read_b128 v[104:107], v38 offset:10256
	ds_read_b128 v[108:111], v38 offset:12288
	ds_read_b128 v[112:115], v38 offset:12304
	ds_read_b128 v[116:119], v38 offset:14336
	ds_read_b128 v[120:123], v38 offset:14352
	ds_read_b128 v[124:127], v38 offset:16384
	ds_read_b128 v[128:131], v38 offset:16400
	s_waitcnt lgkmcnt(14)
	v_mov_b32_e32 v38, v63
	v_mov_b32_e32 v44, v71
	s_waitcnt lgkmcnt(13)
	v_mov_b32_e32 v160, v79
	s_waitcnt lgkmcnt(11)
	v_mov_b32_e32 v162, v87
	s_waitcnt lgkmcnt(9)
	v_mov_b32_e32 v164, v95
	s_waitcnt lgkmcnt(7)
	v_mov_b32_e32 v166, v103
	s_waitcnt lgkmcnt(5)
	v_mov_b32_e32 v168, v111
	s_waitcnt lgkmcnt(3)
	v_mov_b32_e32 v170, v119
	s_waitcnt lgkmcnt(1)
	v_mov_b32_e32 v172, v127
	s_add_i32 s30, s30, 32
	v_mov_b32_e32 v174, v67
	v_mov_b32_e32 v176, v75
	v_mov_b32_e32 v178, v83
	v_mov_b32_e32 v180, v91
	v_mov_b32_e32 v182, v99
	v_mov_b32_e32 v184, v107
	v_mov_b32_e32 v186, v115
	v_mov_b32_e32 v188, v123
	s_waitcnt lgkmcnt(0)
	v_mov_b32_e32 v190, v131
	s_waitcnt vmcnt(7)
	v_pk_fma_f32 v[20:21], v[60:61], v[192:193], v[20:21] op_sel_hi:[0,1,1]
	v_pk_fma_f32 v[22:23], v[60:61], v[194:195], v[22:23] op_sel_hi:[0,1,1]
	v_pk_fma_f32 v[32:33], v[192:193], v[68:69], v[32:33] op_sel_hi:[1,0,1]
	v_pk_fma_f32 v[34:35], v[194:195], v[68:69], v[34:35] op_sel_hi:[1,0,1]
	v_pk_fma_f32 v[28:29], v[192:193], v[76:77], v[28:29] op_sel_hi:[1,0,1]
	v_pk_fma_f32 v[30:31], v[194:195], v[76:77], v[30:31] op_sel_hi:[1,0,1]
	v_pk_fma_f32 v[24:25], v[192:193], v[84:85], v[24:25] op_sel_hi:[1,0,1]
	v_pk_fma_f32 v[26:27], v[194:195], v[84:85], v[26:27] op_sel_hi:[1,0,1]
	v_pk_fma_f32 v[16:17], v[192:193], v[92:93], v[16:17] op_sel_hi:[1,0,1]
	v_pk_fma_f32 v[18:19], v[194:195], v[92:93], v[18:19] op_sel_hi:[1,0,1]
	v_pk_fma_f32 v[12:13], v[192:193], v[100:101], v[12:13] op_sel_hi:[1,0,1]
	v_pk_fma_f32 v[14:15], v[194:195], v[100:101], v[14:15] op_sel_hi:[1,0,1]
	v_pk_fma_f32 v[8:9], v[192:193], v[108:109], v[8:9] op_sel_hi:[1,0,1]
	v_pk_fma_f32 v[10:11], v[194:195], v[108:109], v[10:11] op_sel_hi:[1,0,1]
	v_pk_fma_f32 v[4:5], v[192:193], v[116:117], v[4:5] op_sel_hi:[1,0,1]
	v_pk_fma_f32 v[6:7], v[194:195], v[116:117], v[6:7] op_sel_hi:[1,0,1]
	v_pk_fma_f32 v[0:1], v[192:193], v[124:125], v[0:1] op_sel_hi:[1,0,1]
	v_pk_fma_f32 v[2:3], v[194:195], v[124:125], v[2:3] op_sel_hi:[1,0,1]
	s_waitcnt vmcnt(6)
	v_pk_fma_f32 v[20:21], v[60:61], v[196:197], v[20:21] op_sel:[1,0,0]
	v_pk_fma_f32 v[22:23], v[60:61], v[198:199], v[22:23] op_sel:[1,0,0]
	v_pk_fma_f32 v[32:33], v[196:197], v[68:69], v[32:33] op_sel:[0,1,0]
	v_pk_fma_f32 v[34:35], v[198:199], v[68:69], v[34:35] op_sel:[0,1,0]
	v_pk_fma_f32 v[28:29], v[196:197], v[76:77], v[28:29] op_sel:[0,1,0]
	v_pk_fma_f32 v[30:31], v[198:199], v[76:77], v[30:31] op_sel:[0,1,0]
	v_pk_fma_f32 v[24:25], v[196:197], v[84:85], v[24:25] op_sel:[0,1,0]
	v_pk_fma_f32 v[26:27], v[198:199], v[84:85], v[26:27] op_sel:[0,1,0]
	v_pk_fma_f32 v[16:17], v[196:197], v[92:93], v[16:17] op_sel:[0,1,0]
	v_pk_fma_f32 v[18:19], v[198:199], v[92:93], v[18:19] op_sel:[0,1,0]
	v_pk_fma_f32 v[12:13], v[196:197], v[100:101], v[12:13] op_sel:[0,1,0]
	v_pk_fma_f32 v[14:15], v[198:199], v[100:101], v[14:15] op_sel:[0,1,0]
	v_pk_fma_f32 v[8:9], v[196:197], v[108:109], v[8:9] op_sel:[0,1,0]
	v_pk_fma_f32 v[10:11], v[198:199], v[108:109], v[10:11] op_sel:[0,1,0]
	v_pk_fma_f32 v[4:5], v[196:197], v[116:117], v[4:5] op_sel:[0,1,0]
	v_pk_fma_f32 v[6:7], v[198:199], v[116:117], v[6:7] op_sel:[0,1,0]
	v_pk_fma_f32 v[0:1], v[196:197], v[124:125], v[0:1] op_sel:[0,1,0]
	v_pk_fma_f32 v[2:3], v[198:199], v[124:125], v[2:3] op_sel:[0,1,0]
	s_waitcnt vmcnt(5)
	v_pk_fma_f32 v[20:21], v[62:63], v[200:201], v[20:21] op_sel_hi:[0,1,1]
	v_pk_fma_f32 v[22:23], v[62:63], v[202:203], v[22:23] op_sel_hi:[0,1,1]
	v_pk_fma_f32 v[32:33], v[200:201], v[70:71], v[32:33] op_sel_hi:[1,0,1]
	v_pk_fma_f32 v[34:35], v[202:203], v[70:71], v[34:35] op_sel_hi:[1,0,1]
	v_pk_fma_f32 v[28:29], v[200:201], v[78:79], v[28:29] op_sel_hi:[1,0,1]
	v_pk_fma_f32 v[30:31], v[202:203], v[78:79], v[30:31] op_sel_hi:[1,0,1]
	v_pk_fma_f32 v[24:25], v[200:201], v[86:87], v[24:25] op_sel_hi:[1,0,1]
	v_pk_fma_f32 v[26:27], v[202:203], v[86:87], v[26:27] op_sel_hi:[1,0,1]
	v_pk_fma_f32 v[16:17], v[200:201], v[94:95], v[16:17] op_sel_hi:[1,0,1]
	v_pk_fma_f32 v[18:19], v[202:203], v[94:95], v[18:19] op_sel_hi:[1,0,1]
	v_pk_fma_f32 v[12:13], v[200:201], v[102:103], v[12:13] op_sel_hi:[1,0,1]
	v_pk_fma_f32 v[14:15], v[202:203], v[102:103], v[14:15] op_sel_hi:[1,0,1]
	v_pk_fma_f32 v[8:9], v[200:201], v[110:111], v[8:9] op_sel_hi:[1,0,1]
	v_pk_fma_f32 v[10:11], v[202:203], v[110:111], v[10:11] op_sel_hi:[1,0,1]
	v_pk_fma_f32 v[4:5], v[200:201], v[118:119], v[4:5] op_sel_hi:[1,0,1]
	v_pk_fma_f32 v[6:7], v[202:203], v[118:119], v[6:7] op_sel_hi:[1,0,1]
	v_pk_fma_f32 v[0:1], v[200:201], v[126:127], v[0:1] op_sel_hi:[1,0,1]
	v_pk_fma_f32 v[2:3], v[202:203], v[126:127], v[2:3] op_sel_hi:[1,0,1]
	s_waitcnt vmcnt(4)
	v_pk_fma_f32 v[20:21], v[38:39], v[204:205], v[20:21] op_sel_hi:[0,1,1]
	v_pk_fma_f32 v[22:23], v[38:39], v[206:207], v[22:23] op_sel_hi:[0,1,1]
	v_pk_fma_f32 v[32:33], v[204:205], v[44:45], v[32:33] op_sel_hi:[1,0,1]
	v_pk_fma_f32 v[34:35], v[206:207], v[44:45], v[34:35] op_sel_hi:[1,0,1]
	v_pk_fma_f32 v[28:29], v[204:205], v[160:161], v[28:29] op_sel_hi:[1,0,1]
	v_pk_fma_f32 v[30:31], v[206:207], v[160:161], v[30:31] op_sel_hi:[1,0,1]
	v_pk_fma_f32 v[24:25], v[204:205], v[162:163], v[24:25] op_sel_hi:[1,0,1]
	v_pk_fma_f32 v[26:27], v[206:207], v[162:163], v[26:27] op_sel_hi:[1,0,1]
	v_pk_fma_f32 v[16:17], v[204:205], v[164:165], v[16:17] op_sel_hi:[1,0,1]
	v_pk_fma_f32 v[18:19], v[206:207], v[164:165], v[18:19] op_sel_hi:[1,0,1]
	v_pk_fma_f32 v[12:13], v[204:205], v[166:167], v[12:13] op_sel_hi:[1,0,1]
	v_pk_fma_f32 v[14:15], v[206:207], v[166:167], v[14:15] op_sel_hi:[1,0,1]
	v_pk_fma_f32 v[8:9], v[204:205], v[168:169], v[8:9] op_sel_hi:[1,0,1]
	v_pk_fma_f32 v[10:11], v[206:207], v[168:169], v[10:11] op_sel_hi:[1,0,1]
	v_pk_fma_f32 v[4:5], v[204:205], v[170:171], v[4:5] op_sel_hi:[1,0,1]
	v_pk_fma_f32 v[6:7], v[206:207], v[170:171], v[6:7] op_sel_hi:[1,0,1]
	v_pk_fma_f32 v[0:1], v[204:205], v[172:173], v[0:1] op_sel_hi:[1,0,1]
	v_pk_fma_f32 v[2:3], v[206:207], v[172:173], v[2:3] op_sel_hi:[1,0,1]
	s_waitcnt vmcnt(3)
	v_pk_fma_f32 v[20:21], v[64:65], v[208:209], v[20:21] op_sel_hi:[0,1,1]
	v_pk_fma_f32 v[22:23], v[64:65], v[210:211], v[22:23] op_sel_hi:[0,1,1]
	v_pk_fma_f32 v[32:33], v[208:209], v[72:73], v[32:33] op_sel_hi:[1,0,1]
	v_pk_fma_f32 v[34:35], v[210:211], v[72:73], v[34:35] op_sel_hi:[1,0,1]
	v_pk_fma_f32 v[28:29], v[208:209], v[80:81], v[28:29] op_sel_hi:[1,0,1]
	v_pk_fma_f32 v[30:31], v[210:211], v[80:81], v[30:31] op_sel_hi:[1,0,1]
	v_pk_fma_f32 v[24:25], v[208:209], v[88:89], v[24:25] op_sel_hi:[1,0,1]
	v_pk_fma_f32 v[26:27], v[210:211], v[88:89], v[26:27] op_sel_hi:[1,0,1]
	v_pk_fma_f32 v[16:17], v[208:209], v[96:97], v[16:17] op_sel_hi:[1,0,1]
	v_pk_fma_f32 v[18:19], v[210:211], v[96:97], v[18:19] op_sel_hi:[1,0,1]
	v_pk_fma_f32 v[12:13], v[208:209], v[104:105], v[12:13] op_sel_hi:[1,0,1]
	v_pk_fma_f32 v[14:15], v[210:211], v[104:105], v[14:15] op_sel_hi:[1,0,1]
	v_pk_fma_f32 v[8:9], v[208:209], v[112:113], v[8:9] op_sel_hi:[1,0,1]
	v_pk_fma_f32 v[10:11], v[210:211], v[112:113], v[10:11] op_sel_hi:[1,0,1]
	v_pk_fma_f32 v[4:5], v[208:209], v[120:121], v[4:5] op_sel_hi:[1,0,1]
	v_pk_fma_f32 v[6:7], v[210:211], v[120:121], v[6:7] op_sel_hi:[1,0,1]
	v_pk_fma_f32 v[0:1], v[208:209], v[128:129], v[0:1] op_sel_hi:[1,0,1]
	v_pk_fma_f32 v[2:3], v[210:211], v[128:129], v[2:3] op_sel_hi:[1,0,1]
	s_waitcnt vmcnt(2)
	v_pk_fma_f32 v[20:21], v[64:65], v[212:213], v[20:21] op_sel:[1,0,0]
	v_pk_fma_f32 v[22:23], v[64:65], v[214:215], v[22:23] op_sel:[1,0,0]
	v_pk_fma_f32 v[32:33], v[212:213], v[72:73], v[32:33] op_sel:[0,1,0]
	v_pk_fma_f32 v[34:35], v[214:215], v[72:73], v[34:35] op_sel:[0,1,0]
	v_pk_fma_f32 v[28:29], v[212:213], v[80:81], v[28:29] op_sel:[0,1,0]
	v_pk_fma_f32 v[30:31], v[214:215], v[80:81], v[30:31] op_sel:[0,1,0]
	v_pk_fma_f32 v[24:25], v[212:213], v[88:89], v[24:25] op_sel:[0,1,0]
	v_pk_fma_f32 v[26:27], v[214:215], v[88:89], v[26:27] op_sel:[0,1,0]
	v_pk_fma_f32 v[16:17], v[212:213], v[96:97], v[16:17] op_sel:[0,1,0]
	v_pk_fma_f32 v[18:19], v[214:215], v[96:97], v[18:19] op_sel:[0,1,0]
	v_pk_fma_f32 v[12:13], v[212:213], v[104:105], v[12:13] op_sel:[0,1,0]
	v_pk_fma_f32 v[14:15], v[214:215], v[104:105], v[14:15] op_sel:[0,1,0]
	v_pk_fma_f32 v[8:9], v[212:213], v[112:113], v[8:9] op_sel:[0,1,0]
	v_pk_fma_f32 v[10:11], v[214:215], v[112:113], v[10:11] op_sel:[0,1,0]
	v_pk_fma_f32 v[4:5], v[212:213], v[120:121], v[4:5] op_sel:[0,1,0]
	v_pk_fma_f32 v[6:7], v[214:215], v[120:121], v[6:7] op_sel:[0,1,0]
	v_pk_fma_f32 v[0:1], v[212:213], v[128:129], v[0:1] op_sel:[0,1,0]
	v_pk_fma_f32 v[2:3], v[214:215], v[128:129], v[2:3] op_sel:[0,1,0]
	s_waitcnt vmcnt(1)
	v_pk_fma_f32 v[20:21], v[66:67], v[216:217], v[20:21] op_sel_hi:[0,1,1]
	v_pk_fma_f32 v[22:23], v[66:67], v[218:219], v[22:23] op_sel_hi:[0,1,1]
	v_pk_fma_f32 v[32:33], v[216:217], v[74:75], v[32:33] op_sel_hi:[1,0,1]
	v_pk_fma_f32 v[34:35], v[218:219], v[74:75], v[34:35] op_sel_hi:[1,0,1]
	v_pk_fma_f32 v[28:29], v[216:217], v[82:83], v[28:29] op_sel_hi:[1,0,1]
	v_pk_fma_f32 v[30:31], v[218:219], v[82:83], v[30:31] op_sel_hi:[1,0,1]
	v_pk_fma_f32 v[24:25], v[216:217], v[90:91], v[24:25] op_sel_hi:[1,0,1]
	v_pk_fma_f32 v[26:27], v[218:219], v[90:91], v[26:27] op_sel_hi:[1,0,1]
	v_pk_fma_f32 v[16:17], v[216:217], v[98:99], v[16:17] op_sel_hi:[1,0,1]
	v_pk_fma_f32 v[18:19], v[218:219], v[98:99], v[18:19] op_sel_hi:[1,0,1]
	v_pk_fma_f32 v[12:13], v[216:217], v[106:107], v[12:13] op_sel_hi:[1,0,1]
	v_pk_fma_f32 v[14:15], v[218:219], v[106:107], v[14:15] op_sel_hi:[1,0,1]
	v_pk_fma_f32 v[8:9], v[216:217], v[114:115], v[8:9] op_sel_hi:[1,0,1]
	v_pk_fma_f32 v[10:11], v[218:219], v[114:115], v[10:11] op_sel_hi:[1,0,1]
	v_pk_fma_f32 v[4:5], v[216:217], v[122:123], v[4:5] op_sel_hi:[1,0,1]
	v_pk_fma_f32 v[6:7], v[218:219], v[122:123], v[6:7] op_sel_hi:[1,0,1]
	v_pk_fma_f32 v[0:1], v[216:217], v[130:131], v[0:1] op_sel_hi:[1,0,1]
	v_pk_fma_f32 v[2:3], v[218:219], v[130:131], v[2:3] op_sel_hi:[1,0,1]
	s_waitcnt vmcnt(0)
	v_pk_fma_f32 v[20:21], v[174:175], v[220:221], v[20:21] op_sel_hi:[0,1,1]
	v_pk_fma_f32 v[22:23], v[174:175], v[222:223], v[22:23] op_sel_hi:[0,1,1]
	v_pk_fma_f32 v[32:33], v[220:221], v[176:177], v[32:33] op_sel_hi:[1,0,1]
	v_pk_fma_f32 v[34:35], v[222:223], v[176:177], v[34:35] op_sel_hi:[1,0,1]
	v_pk_fma_f32 v[28:29], v[220:221], v[178:179], v[28:29] op_sel_hi:[1,0,1]
	v_pk_fma_f32 v[30:31], v[222:223], v[178:179], v[30:31] op_sel_hi:[1,0,1]
	v_pk_fma_f32 v[24:25], v[220:221], v[180:181], v[24:25] op_sel_hi:[1,0,1]
	v_pk_fma_f32 v[26:27], v[222:223], v[180:181], v[26:27] op_sel_hi:[1,0,1]
	v_pk_fma_f32 v[16:17], v[220:221], v[182:183], v[16:17] op_sel_hi:[1,0,1]
	v_pk_fma_f32 v[18:19], v[222:223], v[182:183], v[18:19] op_sel_hi:[1,0,1]
	v_pk_fma_f32 v[12:13], v[220:221], v[184:185], v[12:13] op_sel_hi:[1,0,1]
	v_pk_fma_f32 v[14:15], v[222:223], v[184:185], v[14:15] op_sel_hi:[1,0,1]
	v_pk_fma_f32 v[8:9], v[220:221], v[186:187], v[8:9] op_sel_hi:[1,0,1]
	v_pk_fma_f32 v[10:11], v[222:223], v[186:187], v[10:11] op_sel_hi:[1,0,1]
	v_pk_fma_f32 v[4:5], v[220:221], v[188:189], v[4:5] op_sel_hi:[1,0,1]
	v_pk_fma_f32 v[6:7], v[222:223], v[188:189], v[6:7] op_sel_hi:[1,0,1]
	v_pk_fma_f32 v[0:1], v[220:221], v[190:191], v[0:1] op_sel_hi:[1,0,1]
	v_pk_fma_f32 v[2:3], v[222:223], v[190:191], v[2:3] op_sel_hi:[1,0,1]
	ds_write_b128 v47, v[20:23] offset:18432
	ds_write_b128 v47, v[32:35] offset:19456
	ds_write_b128 v47, v[28:31] offset:20480
	ds_write_b128 v47, v[24:27] offset:21504
	ds_write_b128 v47, v[16:19] offset:22528
	ds_write_b128 v47, v[12:15] offset:23552
	ds_write_b128 v47, v[8:11] offset:24576
	ds_write_b128 v47, v[4:7] offset:25600
	ds_write_b128 v47, v[0:3] offset:26624
	s_waitcnt lgkmcnt(0)
	s_barrier
	s_and_saveexec_b64 s[28:29], s[8:9]
	s_cbranch_execz .LBB0_10
	s_add_u32 s26, s83, s26
	s_addc_u32 s27, s84, s27
	s_lshl_b32 s30, s66, 1
	s_add_i32 s64, s30, s72
	s_mul_i32 s64, s64, 9
	s_mov_b64 s[72:73], -1
	v_mov_b32_e32 v0, v36
	s_and_saveexec_b64 s[30:31], s[18:19]
	s_cbranch_execz .LBB0_38
	v_mov_b64_e32 v[0:1], v[36:37]
	s_and_saveexec_b64 s[72:73], s[20:21]
	s_cbranch_execz .LBB0_35
	s_mov_b64 s[74:75], 0
	v_mov_b32_e32 v2, v52
	v_mov_b64_e32 v[0:1], v[36:37]

.LBB0_61:
	s_or_b64 exec, exec, s[6:7]
	s_cmpk_gt_u32 s90, 0xff
	s_cbranch_scc1 .LBB0_116
	s_waitcnt lgkmcnt(0)
	s_cmpk_lt_u32 s2, 0x80
	s_cbranch_scc1 .Lmy_p0_heavy
	s_sub_i32 s6, s2, 0x80
	s_lshl_b32 s6, s6, 2
	s_add_i32 s38, s33, s6
	s_add_i32 s38, s38, 0x400
	s_movk_i32 s3, 0x1220
	s_branch .Lmy_p0_go
.Lmy_p0_heavy:
	s_lshl_b32 s6, s2, 2
	s_add_i32 s38, s33, s6
	s_movk_i32 s3, 0x400
.Lmy_p0_go:
	s_cmp_ge_i32 s38, s3
	s_cbranch_scc1 .LBB0_116
	s_lshl_b32 s39, s62, 1
	s_add_u32 s40, s70, 0x33d8000
	s_addc_u32 s41, s71, 0
	s_add_u32 s42, s70, 0x233d8000
	s_addc_u32 s43, s71, 0
	s_add_u32 s6, s70, 0x2bd8000
	s_addc_u32 s7, s71, 0
	s_add_u32 s8, s70, 0x21d8000
	s_addc_u32 s9, s71, 0
	s_add_u32 s10, s70, 0x19d8000
	s_addc_u32 s11, s71, 0
	s_add_u32 s12, s70, 0xa18000
	s_addc_u32 s13, s71, 0
	v_and_b32_e32 v4, 63, v46
	s_add_u32 s14, s70, 0x218000
	s_addc_u32 s15, s71, 0
	v_lshlrev_b32_e32 v5, 2, v4
	s_lshl_b32 s16, s38, 8
	v_and_b32_e32 v6, 0x7c, v5
	s_add_i32 s52, s16, 0xfff1e000
	s_lshl_b32 s53, s62, 9
	s_mov_b32 s17, 0
	v_mov_b32_e32 v1, 0
	s_movk_i32 s54, 0x2000
	s_movk_i32 s55, 0x4000
	s_movk_i32 s63, 0x6000
	s_mov_b32 s70, 0x8000
	s_mov_b32 s71, 0xa000
	s_mov_b32 s72, 0xc000
	s_mov_b32 s73, 0xe000
	s_mov_b32 s74, 0x10000
	s_mov_b32 s75, 0x12000
	s_mov_b32 s76, 0x14000
	s_mov_b32 s77, 0x16000
	s_mov_b32 s78, 0x18000
	s_mov_b32 s79, 0x1a000
	s_mov_b32 s80, 0x1c000
	s_mov_b32 s81, 0x1e000
	s_movk_i32 s82, 0x7f
	s_movk_i32 s83, 0x2ff
	s_branch .LBB0_66

.LBB0_2405:
	s_and_b32 s29, s12, 3
	v_add_u32_e32 v188, s20, v194
	s_lshl_b32 s20, s23, 2
	s_lshl_b32 s12, s29, 3
	s_and_b32 s20, s20, 4
	s_or_b32 s12, s12, s20
	s_or_b32 s24, s12, s33
	s_lshl_b32 s12, s24, 7
	v_lshl_add_u64 v[2:3], v[172:173], 0, s[12:13]
	v_ashrrev_i32_e32 v189, 31, v188
	s_lshl_b32 s12, s26, 6
	v_lshlrev_b64 v[4:5], 12, v[188:189]
	v_add_u32_e32 v186, 32, v188
	s_lshl_b32 s34, s24, 2
	s_add_i32 s28, s26, s21
	s_sub_i32 s12, s27, s12
	v_lshl_add_u64 v[4:5], v[2:3], 0, v[4:5]
	v_ashrrev_i32_e32 v187, 31, v186
	s_cmp_gt_i32 s26, 0
	global_load_dwordx4 v[130:133], v[4:5], off
	global_load_dwordx4 v[134:137], v[4:5], off offset:32
	global_load_dwordx4 v[138:141], v[4:5], off offset:64
	global_load_dwordx4 v[142:145], v[4:5], off offset:96
	v_lshlrev_b64 v[4:5], 12, v[186:187]
	s_cselect_b32 s30, s25, s12
	v_lshl_add_u64 v[4:5], v[2:3], 0, v[4:5]
	v_add_u32_e32 v2, s30, v196
	v_ashrrev_i32_e32 v3, 31, v2
	v_lshlrev_b64 v[2:3], 9, v[2:3]
	v_lshl_add_u64 v[2:3], s[8:9], 0, v[2:3]
	s_lshl_b32 s12, s29, 7
	s_lshl_b32 s20, s29, 6
	v_lshl_add_u64 v[2:3], v[2:3], 0, s[12:13]
	v_lshl_add_u64 v[6:7], v[174:175], 1, v[2:3]
	v_add_u32_e32 v2, s20, v197
	v_ashrrev_i32_e32 v3, 31, v2
	v_lshlrev_b64 v[2:3], 15, v[2:3]
	v_lshl_add_u64 v[8:9], s[10:11], 0, v[2:3]
	s_ashr_i32 s31, s30, 31
	v_lshl_add_u64 v[8:9], s[30:31], 1, v[8:9]
	global_load_dwordx4 v[146:149], v[4:5], off
	global_load_dwordx4 v[150:153], v[4:5], off offset:32
	v_lshl_add_u64 v[8:9], v[8:9], 0, v[184:185]
	global_load_dwordx4 v[162:165], v[6:7], off
	global_load_dwordx4 v[166:169], v[8:9], off
	v_mov_b32_e32 v6, s34
	s_waitcnt lgkmcnt(0)
	global_load_dword v1, v6, s[14:15]
	global_load_dwordx4 v[154:157], v[4:5], off offset:64
	global_load_dwordx4 v[158:161], v[4:5], off offset:96
	s_cmp_lt_i32 s28, 1
	s_waitcnt vmcnt(4)
	ds_write_b128 v204, v[162:165]
	s_waitcnt vmcnt(3)
	ds_write2_b64 v205, v[166:167], v[168:169] offset1:1
	s_waitcnt lgkmcnt(0)
	s_barrier
	s_cbranch_scc1 .LBB0_2398
	s_waitcnt vmcnt(0)
	v_mul_f32_e32 v224, 0x3fb8aa3b, v1
	v_lshl_add_u64 v[192:193], v[178:179], 0, v[2:3]
	v_add_u32_e32 v1, s19, v180
	v_add_u32_e32 v2, s18, v194
	v_mov_b32_e32 v14, v0
	v_mov_b32_e32 v15, v0
	v_sub_u32_e32 v210, v1, v2
	v_mov_b32_e32 v1, v0
	v_mov_b32_e32 v2, v0
	v_mov_b32_e32 v3, v0
	v_mov_b32_e32 v4, v0
	v_mov_b32_e32 v5, v0
	v_mov_b32_e32 v6, v0
	v_mov_b32_e32 v7, v0
	v_mov_b32_e32 v8, v0
	v_mov_b32_e32 v9, v0
	v_mov_b32_e32 v10, v0
	v_mov_b32_e32 v11, v0
	v_mov_b32_e32 v12, v0
	v_mov_b32_e32 v13, v0
	v_mov_b64_e32 v[64:65], v[14:15]
	v_mov_b64_e32 v[48:49], v[14:15]
	v_mov_b64_e32 v[32:33], v[14:15]
	s_lshl_b32 s12, s20, 1
	v_mov_b64_e32 v[62:63], v[12:13]
	v_mov_b64_e32 v[60:61], v[10:11]
	v_mov_b64_e32 v[58:59], v[8:9]
	v_mov_b64_e32 v[56:57], v[6:7]
	v_mov_b64_e32 v[54:55], v[4:5]
	v_mov_b64_e32 v[52:53], v[2:3]
	v_mov_b64_e32 v[50:51], v[0:1]
	v_mov_b64_e32 v[46:47], v[12:13]
	v_mov_b64_e32 v[44:45], v[10:11]
	v_mov_b64_e32 v[42:43], v[8:9]
	v_mov_b64_e32 v[40:41], v[6:7]
	v_mov_b64_e32 v[38:39], v[4:5]
	v_mov_b64_e32 v[36:37], v[2:3]
	v_mov_b64_e32 v[34:35], v[0:1]
	v_mov_b64_e32 v[30:31], v[12:13]
	v_mov_b64_e32 v[28:29], v[10:11]
	v_mov_b64_e32 v[26:27], v[8:9]
	v_mov_b64_e32 v[24:25], v[6:7]
	v_mov_b64_e32 v[22:23], v[4:5]
	v_mov_b64_e32 v[20:21], v[2:3]
	v_mov_b64_e32 v[18:19], v[0:1]
	v_mov_b64_e32 v[16:17], v[14:15]
	v_lshl_add_u64 v[190:191], v[176:177], 0, s[12:13]
	s_sub_i32 s12, s19, s18
	s_mov_b32 s20, 0
	s_mov_b32 s29, 64
	v_mov_b32_e32 v209, v171
	v_mov_b32_e32 v208, v171
	v_mov_b32_e32 v211, v224
	v_mov_b64_e32 v[14:15], v[12:13]
	v_mov_b64_e32 v[12:13], v[10:11]
	v_mov_b64_e32 v[10:11], v[8:9]
	v_mov_b64_e32 v[8:9], v[6:7]
	v_mov_b64_e32 v[6:7], v[4:5]
	v_mov_b64_e32 v[4:5], v[2:3]
	v_mov_b64_e32 v[2:3], v[0:1]

.LBB0_2409:
	s_and_b32 s31, s20, 1
	s_mul_i32 s21, s31, 0x4600
	s_add_i32 s34, s21, 0
	v_add3_u32 v1, s34, v202, v170
	ds_read_b128 v[66:69], v1
	ds_read_b128 v[212:215], v1 offset:32
	ds_read_b128 v[70:73], v1 offset:4608
	ds_read_b128 v[216:219], v1 offset:4640
	s_cmp_lt_i32 s20, s26
	s_cselect_b64 s[20:21], -1, 0
	s_waitcnt lgkmcnt(3)
	v_mfma_f32_32x32x16_bf16 v[114:129], v[66:69], v[130:133], 0
	s_add_i32 s35, s12, s29
	s_and_b64 s[20:21], s[16:17], s[20:21]
	s_add_i32 s36, s35, 0xffffff7e
	s_cmp_lt_u32 s36, 0xffffff5d
	s_cselect_b64 s[36:37], -1, 0
	s_and_b64 s[36:37], s[20:21], s[36:37]
	s_andn2_b64 vcc, exec, s[36:37]
	s_waitcnt lgkmcnt(1)
	v_mfma_f32_32x32x16_bf16 v[98:113], v[70:73], v[130:133], 0
	v_mfma_f32_32x32x16_bf16 v[82:97], v[66:69], v[146:149], 0
	v_mfma_f32_32x32x16_bf16 v[66:81], v[70:73], v[146:149], 0
	v_mfma_f32_32x32x16_bf16 v[114:129], v[212:215], v[134:137], v[114:129]
	s_waitcnt lgkmcnt(0)
	v_mfma_f32_32x32x16_bf16 v[98:113], v[216:219], v[134:137], v[98:113]
	v_mfma_f32_32x32x16_bf16 v[82:97], v[212:215], v[150:153], v[82:97]
	v_mfma_f32_32x32x16_bf16 v[66:81], v[216:219], v[150:153], v[66:81]
	ds_read_b128 v[212:215], v1 offset:64
	ds_read_b128 v[216:219], v1 offset:96
	ds_read_b128 v[220:223], v1 offset:4672
	ds_read_b128 v[232:235], v1 offset:4704
	s_waitcnt lgkmcnt(3)
	v_mfma_f32_32x32x16_bf16 v[114:129], v[212:215], v[138:141], v[114:129]
	s_waitcnt lgkmcnt(1)
	v_mfma_f32_32x32x16_bf16 v[98:113], v[220:223], v[138:141], v[98:113]
	v_mfma_f32_32x32x16_bf16 v[82:97], v[212:215], v[154:157], v[82:97]
	v_add_u32_e32 v213, s29, v210
	v_add_u32_e32 v230, 64, v213
	v_add_u32_e32 v229, 0x41, v213
	v_add_u32_e32 v228, 0x42, v213
	v_add_u32_e32 v227, 0x43, v213
	v_add_u32_e32 v226, 0x48, v213
	v_add_u32_e32 v225, 0x49, v213
	v_mfma_f32_32x32x16_bf16 v[66:81], v[220:223], v[154:157], v[66:81]
	v_add_u32_e32 v223, 0x4a, v213
	v_add_u32_e32 v222, 0x4b, v213
	v_add_u32_e32 v221, 0x50, v213
	v_add_u32_e32 v220, 0x51, v213
	v_add_u32_e32 v215, 0x5a, v213
	v_add_u32_e32 v214, 0x5b, v213
	v_mfma_f32_32x32x16_bf16 v[114:129], v[216:219], v[142:145], v[114:129]
	s_waitcnt lgkmcnt(0)
	v_mfma_f32_32x32x16_bf16 v[98:113], v[232:235], v[142:145], v[98:113]
	v_mfma_f32_32x32x16_bf16 v[82:97], v[216:219], v[158:161], v[82:97]
	v_add_u32_e32 v219, 0x52, v213
	v_add_u32_e32 v218, 0x53, v213
	v_add_u32_e32 v217, 0x58, v213
	v_add_u32_e32 v216, 0x59, v213
	v_mfma_f32_32x32x16_bf16 v[66:81], v[232:235], v[158:161], v[66:81]
	s_cbranch_vccnz .LBB0_2411
	v_cmp_gt_u32_e32 vcc, s22, v230
	v_add_u32_e32 v1, 0x60, v213
	s_nop 0
	v_cndmask_b32_e32 v114, v207, v114, vcc
	v_cmp_gt_u32_e32 vcc, s22, v1
	v_add_u32_e32 v1, 0x61, v213
	s_nop 0
	v_cndmask_b32_e32 v98, v207, v98, vcc
	v_cmp_gt_u32_e32 vcc, s22, v229
	s_nop 1
	v_cndmask_b32_e32 v115, v207, v115, vcc
	v_cmp_gt_u32_e32 vcc, s22, v1
	v_add_u32_e32 v1, 0x62, v213
	s_nop 0
	v_cndmask_b32_e32 v99, v207, v99, vcc
	v_cmp_gt_u32_e32 vcc, s22, v228
	s_nop 1
	v_cndmask_b32_e32 v116, v207, v116, vcc
	v_cmp_gt_u32_e32 vcc, s22, v1
	v_add_u32_e32 v1, 0x63, v213
	s_nop 0
	v_cndmask_b32_e32 v100, v207, v100, vcc
	v_cmp_gt_u32_e32 vcc, s22, v227
	s_nop 1
	v_cndmask_b32_e32 v117, v207, v117, vcc
	v_cmp_gt_u32_e32 vcc, s22, v1
	v_add_u32_e32 v1, 0x68, v213
	s_nop 0
	v_cndmask_b32_e32 v101, v207, v101, vcc
	v_cmp_gt_u32_e32 vcc, s22, v226
	s_nop 1
	v_cndmask_b32_e32 v118, v207, v118, vcc
	v_cmp_gt_u32_e32 vcc, s22, v1
	v_add_u32_e32 v1, 0x69, v213
	s_nop 0
	v_cndmask_b32_e32 v102, v207, v102, vcc
	v_cmp_gt_u32_e32 vcc, s22, v225
	s_nop 1
	v_cndmask_b32_e32 v119, v207, v119, vcc
	v_cmp_gt_u32_e32 vcc, s22, v1
	v_add_u32_e32 v1, 0x6a, v213
	s_nop 0
	v_cndmask_b32_e32 v103, v207, v103, vcc
	v_cmp_gt_u32_e32 vcc, s22, v223
	s_nop 1
	v_cndmask_b32_e32 v120, v207, v120, vcc
	v_cmp_gt_u32_e32 vcc, s22, v1
	v_add_u32_e32 v1, 0x6b, v213
	s_nop 0
	v_cndmask_b32_e32 v104, v207, v104, vcc
	v_cmp_gt_u32_e32 vcc, s22, v222
	s_nop 1
	v_cndmask_b32_e32 v121, v207, v121, vcc
	v_cmp_gt_u32_e32 vcc, s22, v1
	v_add_u32_e32 v1, 0x70, v213
	s_nop 0
	v_cndmask_b32_e32 v105, v207, v105, vcc
	v_cmp_gt_u32_e32 vcc, s22, v221
	s_nop 1
	v_cndmask_b32_e32 v122, v207, v122, vcc
	v_cmp_gt_u32_e32 vcc, s22, v1
	v_add_u32_e32 v1, 0x71, v213
	s_nop 0
	v_cndmask_b32_e32 v106, v207, v106, vcc
	v_cmp_gt_u32_e32 vcc, s22, v220
	s_nop 1
	v_cndmask_b32_e32 v123, v207, v123, vcc
	v_cmp_gt_u32_e32 vcc, s22, v1
	v_add_u32_e32 v1, 0x72, v213
	s_nop 0
	v_cndmask_b32_e32 v107, v207, v107, vcc
	v_cmp_gt_u32_e32 vcc, s22, v219
	s_nop 1
	v_cndmask_b32_e32 v124, v207, v124, vcc
	v_cmp_gt_u32_e32 vcc, s22, v1
	v_add_u32_e32 v1, 0x73, v213
	s_nop 0
	v_cndmask_b32_e32 v108, v207, v108, vcc
	v_cmp_gt_u32_e32 vcc, s22, v218
	s_nop 1
	v_cndmask_b32_e32 v125, v207, v125, vcc
	v_cmp_gt_u32_e32 vcc, s22, v1
	v_add_u32_e32 v1, 0x78, v213
	s_nop 0
	v_cndmask_b32_e32 v109, v207, v109, vcc
	v_cmp_gt_u32_e32 vcc, s22, v217
	s_nop 1
	v_cndmask_b32_e32 v126, v207, v126, vcc
	v_cmp_gt_u32_e32 vcc, s22, v1
	v_add_u32_e32 v1, 0x79, v213
	s_nop 0
	v_cndmask_b32_e32 v110, v207, v110, vcc
	v_cmp_gt_u32_e32 vcc, s22, v216
	s_nop 1
	v_cndmask_b32_e32 v127, v207, v127, vcc
	v_cmp_gt_u32_e32 vcc, s22, v1
	v_add_u32_e32 v1, 0x7a, v213
	s_nop 0
	v_cndmask_b32_e32 v111, v207, v111, vcc
	v_cmp_gt_u32_e32 vcc, s22, v215
	s_nop 1
	v_cndmask_b32_e32 v128, v207, v128, vcc
	v_cmp_gt_u32_e32 vcc, s22, v1
	v_add_u32_e32 v1, 0x7b, v213
	s_nop 0
	v_cndmask_b32_e32 v112, v207, v112, vcc
	v_cmp_gt_u32_e32 vcc, s22, v214
	s_nop 1
	v_cndmask_b32_e32 v129, v207, v129, vcc
	v_cmp_gt_u32_e32 vcc, s22, v1
	s_nop 1
	v_cndmask_b32_e32 v113, v207, v113, vcc

.LBB0_2419:
	v_add3_u32 v212, s34, v195, v181
	v_add_u32_e32 v217, 0x2000, v212
	ds_read2_b64 v[230:233], v217 offset0:128 offset1:130
	v_sub_f32_e32 v82, v82, v213
	v_sub_f32_e32 v83, v83, v213
	v_sub_f32_e32 v84, v84, v213
	v_sub_f32_e32 v85, v85, v213
	v_sub_f32_e32 v86, v86, v213
	v_sub_f32_e32 v87, v87, v213
	v_sub_f32_e32 v88, v88, v213
	v_sub_f32_e32 v246, v72, v213
	v_sub_f32_e32 v72, v89, v213
	v_exp_f32_e32 v82, v82
	v_exp_f32_e32 v83, v83
	v_exp_f32_e32 v84, v84
	v_exp_f32_e32 v85, v85
	v_exp_f32_e32 v86, v86
	v_exp_f32_e32 v87, v87
	v_exp_f32_e32 v88, v88
	v_exp_f32_e32 v72, v72
	v_sub_f32_e32 v98, v98, v1
	v_cvt_pk_bf16_f32 v218, v114, v115
	v_cvt_pk_bf16_f32 v219, v116, v117
	v_cvt_pk_bf16_f32 v220, v118, v119
	v_cvt_pk_bf16_f32 v221, v120, v121
	v_cvt_pk_bf16_f32 v234, v82, v83
	v_cvt_pk_bf16_f32 v235, v84, v85
	v_cvt_pk_bf16_f32 v236, v86, v87
	v_cvt_pk_bf16_f32 v237, v88, v72
	ds_read2_b64 v[238:241], v217 offset0:132 offset1:134
	v_exp_f32_e32 v211, v98
	v_sub_f32_e32 v98, v99, v1
	s_waitcnt lgkmcnt(1)
	v_mfma_f32_32x32x16_bf16 v[50:65], v[230:233], v[218:221], v[50:65]
	v_exp_f32_e32 v214, v98
	v_sub_f32_e32 v98, v100, v1
	v_exp_f32_e32 v215, v98
	v_sub_f32_e32 v98, v101, v1
	v_sub_f32_e32 v89, v90, v213
	v_sub_f32_e32 v90, v91, v213
	v_sub_f32_e32 v91, v92, v213
	v_mfma_f32_32x32x16_bf16 v[18:33], v[230:233], v[234:237], v[18:33]
	v_sub_f32_e32 v92, v93, v213
	v_sub_f32_e32 v93, v94, v213
	v_sub_f32_e32 v94, v95, v213
	v_sub_f32_e32 v95, v96, v213
	v_sub_f32_e32 v96, v97, v213
	v_exp_f32_e32 v216, v98
	v_sub_f32_e32 v98, v102, v1
	v_exp_f32_e32 v89, v89
	v_exp_f32_e32 v90, v90
	v_exp_f32_e32 v91, v91
	v_exp_f32_e32 v92, v92
	v_exp_f32_e32 v93, v93
	v_exp_f32_e32 v94, v94
	v_exp_f32_e32 v95, v95
	v_exp_f32_e32 v96, v96
	v_exp_f32_e32 v102, v98
	v_sub_f32_e32 v98, v103, v1
	v_exp_f32_e32 v103, v98
	v_sub_f32_e32 v98, v104, v1
	v_exp_f32_e32 v104, v98
	v_sub_f32_e32 v98, v105, v1
	v_exp_f32_e32 v105, v98
	v_sub_f32_e32 v98, v106, v1
	v_cvt_pk_bf16_f32 v222, v122, v123
	v_cvt_pk_bf16_f32 v223, v124, v125
	v_cvt_pk_bf16_f32 v224, v126, v127
	v_cvt_pk_bf16_f32 v225, v128, v129
	v_cvt_pk_bf16_f32 v230, v89, v90
	v_cvt_pk_bf16_f32 v231, v91, v92
	v_cvt_pk_bf16_f32 v232, v93, v94
	v_cvt_pk_bf16_f32 v233, v95, v96
	ds_read2_b64 v[242:245], v217 offset0:136 offset1:138
	v_exp_f32_e32 v106, v98
	v_sub_f32_e32 v98, v107, v1
	s_waitcnt lgkmcnt(1)
	v_mfma_f32_32x32x16_bf16 v[50:65], v[238:241], v[222:225], v[50:65]
	v_exp_f32_e32 v107, v98
	v_sub_f32_e32 v98, v108, v1
	v_exp_f32_e32 v108, v98
	v_sub_f32_e32 v98, v109, v1
	v_sub_f32_e32 v66, v66, v213
	v_sub_f32_e32 v67, v67, v213
	v_sub_f32_e32 v68, v68, v213
	v_mfma_f32_32x32x16_bf16 v[18:33], v[238:241], v[230:233], v[18:33]
	v_sub_f32_e32 v69, v69, v213
	v_sub_f32_e32 v70, v70, v213
	v_sub_f32_e32 v71, v71, v213
	v_sub_f32_e32 v73, v73, v213
	v_exp_f32_e32 v109, v98
	v_sub_f32_e32 v98, v110, v1
	v_exp_f32_e32 v66, v66
	v_exp_f32_e32 v67, v67
	v_exp_f32_e32 v68, v68
	v_exp_f32_e32 v69, v69
	v_exp_f32_e32 v70, v70
	v_exp_f32_e32 v71, v71
	v_exp_f32_e32 v97, v246
	v_exp_f32_e32 v73, v73
	v_exp_f32_e32 v110, v98
	v_sub_f32_e32 v98, v111, v1
	v_exp_f32_e32 v111, v98
	v_sub_f32_e32 v98, v112, v1
	v_exp_f32_e32 v112, v98
	v_sub_f32_e32 v98, v113, v1
	v_exp_f32_e32 v113, v98
	v_cvt_pk_bf16_f32 v98, v211, v214
	v_cvt_pk_bf16_f32 v99, v215, v216
	v_cvt_pk_bf16_f32 v100, v102, v103
	v_cvt_pk_bf16_f32 v101, v104, v105
	v_cvt_pk_bf16_f32 v238, v66, v67
	v_cvt_pk_bf16_f32 v239, v68, v69
	v_cvt_pk_bf16_f32 v240, v70, v71
	v_cvt_pk_bf16_f32 v241, v97, v73
	ds_read2_b64 v[246:249], v217 offset0:140 offset1:142
	s_waitcnt lgkmcnt(1)
	v_mfma_f32_32x32x16_bf16 v[50:65], v[242:245], v[98:101], v[50:65]
	v_sub_f32_e32 v74, v74, v213
	v_sub_f32_e32 v75, v75, v213
	v_sub_f32_e32 v76, v76, v213
	v_sub_f32_e32 v77, v77, v213
	v_sub_f32_e32 v78, v78, v213
	v_sub_f32_e32 v79, v79, v213
	v_sub_f32_e32 v80, v80, v213
	v_mfma_f32_32x32x16_bf16 v[18:33], v[242:245], v[238:241], v[18:33]
	v_sub_f32_e32 v81, v81, v213
	v_exp_f32_e32 v74, v74
	v_exp_f32_e32 v75, v75
	v_exp_f32_e32 v76, v76
	v_exp_f32_e32 v77, v77
	v_exp_f32_e32 v78, v78
	v_exp_f32_e32 v79, v79
	v_exp_f32_e32 v80, v80
	v_exp_f32_e32 v81, v81
	v_cvt_pk_bf16_f32 v226, v106, v107
	v_cvt_pk_bf16_f32 v227, v108, v109
	v_cvt_pk_bf16_f32 v228, v110, v111
	v_cvt_pk_bf16_f32 v229, v112, v113
	v_cvt_pk_bf16_f32 v242, v74, v75
	v_cvt_pk_bf16_f32 v243, v76, v77
	v_cvt_pk_bf16_f32 v244, v78, v79
	v_cvt_pk_bf16_f32 v245, v80, v81
	v_add_u32_e32 v212, 0x3000, v212
	s_waitcnt lgkmcnt(0)
	v_mfma_f32_32x32x16_bf16 v[50:65], v[246:249], v[226:229], v[50:65]
	s_andn2_b64 vcc, exec, s[18:19]
	v_mfma_f32_32x32x16_bf16 v[18:33], v[246:249], v[242:245], v[18:33]
	ds_read2_b64 v[246:249], v212 offset0:160 offset1:162
	s_waitcnt lgkmcnt(0)
	v_mfma_f32_32x32x16_bf16 v[34:49], v[246:249], v[218:221], v[34:49]
	ds_read2_b64 v[218:221], v212 offset0:164 offset1:166
	v_mfma_f32_32x32x16_bf16 v[2:17], v[246:249], v[234:237], v[2:17]
	s_waitcnt lgkmcnt(0)
	v_mfma_f32_32x32x16_bf16 v[34:49], v[218:221], v[222:225], v[34:49]
	v_mfma_f32_32x32x16_bf16 v[2:17], v[218:221], v[230:233], v[2:17]
	ds_read2_b64 v[218:221], v212 offset0:168 offset1:170
	s_waitcnt lgkmcnt(0)
	v_mfma_f32_32x32x16_bf16 v[34:49], v[218:221], v[98:101], v[34:49]
	ds_read2_b64 v[98:101], v212 offset0:172 offset1:174
	v_mfma_f32_32x32x16_bf16 v[2:17], v[218:221], v[238:241], v[2:17]
	s_waitcnt lgkmcnt(0)
	v_mfma_f32_32x32x16_bf16 v[34:49], v[98:101], v[226:229], v[34:49]
	v_mfma_f32_32x32x16_bf16 v[2:17], v[98:101], v[242:245], v[2:17]
	s_cbranch_vccnz .LBB0_2421
	s_xor_b32 s18, s31, 1
	s_mulk_i32 s18, 0x4600
	s_add_i32 s18, s18, 0
	v_add_u32_e32 v98, s18, v200
	v_add3_u32 v99, s18, v198, v199
	v_add3_u32 v98, v98, v201, s3
	s_waitcnt vmcnt(1)
	ds_write_b128 v99, v[162:165]
	s_waitcnt vmcnt(0)
	ds_write2_b64 v98, v[166:167], v[168:169] offset1:1
